# baseline (speedup 1.0000x reference)
; #define PG8_STAGE(bufoff, gbase, voff) do { _Pragma("unroll") for (int _i = 0; _i < 2; ++_i) \
;         __builtin_amdgcn_global_load_lds((const unsigned*)((const char*)(gbase) + (voff)[_i]), (PG8_LAS unsigned*)(lds + (bufoff) + ldsw + _i * 8192), 16, 0, 0); } while (0)
; #define PG8_WAIT_V(n) asm volatile("s_waitcnt vmcnt(" #n ")" ::: "memory")
; #define PG8_WAIT_L(n) asm volatile("s_waitcnt lgkmcnt(" #n ")" ::: "memory")
; #define PG8_BAR __builtin_amdgcn_s_barrier()
; #define PG8_SCHED __builtin_amdgcn_sched_barrier(0)
; template <class Epi, class Sched, bool ALIGN_EPI = false, bool SP2 = false, bool FP8 = false>
; __device__ __forceinline__ void gemm_phase(PG8_LAS unsigned char* lds, const Gemm g, const Sched& S, const Epi& E, const int tid) {
;     ...
;             PG8_LDB(B0, 0, 0); PG8_LDB(B1, 0, 1); PG8_SCHED; PG8_LDA(At, 0, 0); PG8_STAGE(PG8_SA(1, 1), a1 + hstepA, voffA);
;             PG8_WAIT_V(8); PG8_WAIT_L(0); PG8_BAR; PG8_MMA(0, 0, At, B0); PG8_MMA(0, 1, At, B1); PG8_BAR; PG8_SCHED;
.Lrot_98:
	ds_read_b128 v[142:145], v153
	ds_read_b128 v[146:149], v153 offset:1024
	ds_read_b128 v[154:157], v153 offset:2048
	ds_read_b128 v[158:161], v153 offset:3072
	v_add_u32_e32 v153, s60, v150
	ds_read_b128 v[180:183], v153
	ds_read_b128 v[184:187], v153 offset:1024
	ds_read_b128 v[188:191], v153 offset:2048
	ds_read_b128 v[192:195], v153 offset:3072
	v_lshl_add_u64 v[200:201], s[34:35], 0, v[138:139]
	s_add_i32 m0, s43, 0xc000
	ds_read_b128 v[196:199], v152
	ds_read_b128 v[220:223], v152 offset:1024
	ds_read_b128 v[224:227], v152 offset:2048
	ds_read_b128 v[228:231], v152 offset:3072
	ds_read_b128 v[232:235], v152 offset:4096
	ds_read_b128 v[236:239], v152 offset:5120
	ds_read_b128 v[240:243], v152 offset:6144
	ds_read_b128 v[244:247], v152 offset:7168
	global_load_lds_dwordx4 v[200:201], off
	v_lshl_add_u64 v[200:201], s[34:35], 0, v[140:141]
	s_add_i32 m0, s43, 0xe000
	s_nop 0
	global_load_lds_dwordx4 v[200:201], off
	s_cmp_eq_i32 s56, -2
	s_cbranch_scc1 .Lskw_0_0
	s_waitcnt vmcnt(8)

; #define PG8_STAGE(bufoff, gbase, voff) do { _Pragma("unroll") for (int _i = 0; _i < 2; ++_i) \
;         __builtin_amdgcn_global_load_lds((const unsigned*)((const char*)(gbase) + (voff)[_i]), (PG8_LAS unsigned*)(lds + (bufoff) + ldsw + _i * 8192), 16, 0, 0); } while (0)
; #define PG8_WAIT_V(n) asm volatile("s_waitcnt vmcnt(" #n ")" ::: "memory")
; #define PG8_WAIT_L(n) asm volatile("s_waitcnt lgkmcnt(" #n ")" ::: "memory")
; #define PG8_BAR __builtin_amdgcn_s_barrier()
; #define PG8_SCHED __builtin_amdgcn_sched_barrier(0)
; template <class Epi, class Sched, bool ALIGN_EPI = false, bool SP2 = false, bool FP8 = false>
; __device__ __forceinline__ void gemm_phase(PG8_LAS unsigned char* lds, const Gemm g, const Sched& S, const Epi& E, const int tid) {
;     ...
;             PG8_WAIT_V(8); PG8_WAIT_L(0); PG8_BAR; PG8_MMA(0, 0, At, B0); PG8_MMA(0, 1, At, B1); PG8_BAR; PG8_SCHED;
;             PG8_LDA(At, 0, 1); PG8_STAGE(PG8_SB(0, 0), b2, voffB); PG8_STAGE(PG8_SB(0, 1), b2 + hstepB, voffB); PG8_STAGE(PG8_SA(0, 0), a2, voffA);
;             PG8_WAIT_V(8); PG8_WAIT_L(0); PG8_BAR; PG8_MMA(1, 0, At, B0); PG8_MMA(1, 1, At, B1); PG8_BAR; PG8_SCHED;
;             PG8_LDB(B0, 1, 0); PG8_LDB(B1, 1, 1); PG8_SCHED; PG8_LDA(At, 1, 0); PG8_STAGE(PG8_SA(0, 1), a2 + hstepA, voffA);
;             PG8_WAIT_V(8); PG8_WAIT_L(0); PG8_BAR; PG8_MMA(0, 0, At, B0); PG8_MMA(0, 1, At, B1); PG8_BAR; PG8_SCHED;
.Lskw_0_1:
	s_waitcnt lgkmcnt(0)
	s_barrier
	s_setprio 1
	s_waitcnt lgkmcnt(0)
	v_mfma_f32_16x16x32_bf16 v[62:65], v[142:145], v[196:199], v[62:65]
	v_mfma_f32_16x16x32_bf16 v[58:61], v[154:157], v[196:199], v[58:61]
	v_mfma_f32_16x16x32_bf16 v[46:49], v[142:145], v[224:227], v[46:49]
	v_mfma_f32_16x16x32_bf16 v[42:45], v[154:157], v[224:227], v[42:45]
	v_mfma_f32_16x16x32_bf16 v[28:31], v[142:145], v[232:235], v[28:31]
	v_mfma_f32_16x16x32_bf16 v[24:27], v[154:157], v[232:235], v[24:27]
	v_mfma_f32_16x16x32_bf16 v[12:15], v[142:145], v[240:243], v[12:15]
	v_mfma_f32_16x16x32_bf16 v[8:11], v[154:157], v[240:243], v[8:11]
	v_mfma_f32_16x16x32_bf16 v[62:65], v[146:149], v[220:223], v[62:65]
	v_mfma_f32_16x16x32_bf16 v[58:61], v[158:161], v[220:223], v[58:61]
	v_mfma_f32_16x16x32_bf16 v[46:49], v[146:149], v[228:231], v[46:49]
	v_mfma_f32_16x16x32_bf16 v[42:45], v[158:161], v[228:231], v[42:45]
	v_mfma_f32_16x16x32_bf16 v[28:31], v[146:149], v[236:239], v[28:31]
	v_mfma_f32_16x16x32_bf16 v[24:27], v[158:161], v[236:239], v[24:27]
	v_mfma_f32_16x16x32_bf16 v[12:15], v[146:149], v[244:247], v[12:15]
	v_mfma_f32_16x16x32_bf16 v[8:11], v[158:161], v[244:247], v[8:11]
	s_setprio 0
	s_setprio 1
	v_mfma_f32_16x16x32_bf16 v[54:57], v[180:183], v[196:199], v[54:57]
	v_mfma_f32_16x16x32_bf16 v[50:53], v[188:191], v[196:199], v[50:53]
	v_mfma_f32_16x16x32_bf16 v[38:41], v[180:183], v[224:227], v[38:41]
	v_mfma_f32_16x16x32_bf16 v[34:37], v[188:191], v[224:227], v[34:37]
	v_mfma_f32_16x16x32_bf16 v[20:23], v[180:183], v[232:235], v[20:23]
	v_mfma_f32_16x16x32_bf16 v[16:19], v[188:191], v[232:235], v[16:19]
	v_mfma_f32_16x16x32_bf16 v[4:7], v[180:183], v[240:243], v[4:7]
	v_mfma_f32_16x16x32_bf16 v[0:3], v[188:191], v[240:243], v[0:3]
	v_mfma_f32_16x16x32_bf16 v[54:57], v[184:187], v[220:223], v[54:57]
	v_mfma_f32_16x16x32_bf16 v[50:53], v[192:195], v[220:223], v[50:53]
	v_mfma_f32_16x16x32_bf16 v[38:41], v[184:187], v[228:231], v[38:41]
	v_mfma_f32_16x16x32_bf16 v[34:37], v[192:195], v[228:231], v[34:37]
	v_mfma_f32_16x16x32_bf16 v[20:23], v[184:187], v[236:239], v[20:23]
	v_mfma_f32_16x16x32_bf16 v[16:19], v[192:195], v[236:239], v[16:19]
	v_mfma_f32_16x16x32_bf16 v[4:7], v[184:187], v[244:247], v[4:7]
	v_mfma_f32_16x16x32_bf16 v[0:3], v[192:195], v[244:247], v[0:3]
	s_setprio 0
	s_barrier
	s_add_i32 s57, 0, 0x18000
	v_add_u32_e32 v153, s57, v150
	s_add_i32 s58, 0, 0x1c000
	ds_read_b128 v[142:145], v153
	ds_read_b128 v[146:149], v153 offset:1024
	ds_read_b128 v[154:157], v153 offset:2048
	ds_read_b128 v[158:161], v153 offset:3072
	v_add_u32_e32 v153, s58, v150
	ds_read_b128 v[180:183], v153
	ds_read_b128 v[184:187], v153 offset:1024
	ds_read_b128 v[188:191], v153 offset:2048
	ds_read_b128 v[192:195], v153 offset:3072
	s_add_u32 s40, s40, 0x80000
	s_addc_u32 s41, s41, 0
	s_mov_b32 m0, s45
	v_lshl_add_u64 v[166:167], s[40:41], 0, v[136:137]
	ds_read_b128 v[196:199], v152 offset:32768
	ds_read_b128 v[220:223], v152 offset:33792
	ds_read_b128 v[224:227], v152 offset:34816
	ds_read_b128 v[228:231], v152 offset:35840
	ds_read_b128 v[232:235], v152 offset:36864
	ds_read_b128 v[236:239], v152 offset:37888
	ds_read_b128 v[240:243], v152 offset:38912
	ds_read_b128 v[244:247], v152 offset:39936
	global_load_lds_dwordx4 v[166:167], off
	v_lshl_add_u64 v[166:167], s[40:41], 0, v[132:133]
	s_mov_b32 m0, s46
	s_nop 0
	global_load_lds_dwordx4 v[166:167], off
	s_waitcnt vmcnt(8)
	s_waitcnt lgkmcnt(0)
	s_barrier
	s_setprio 1
	s_waitcnt lgkmcnt(0)
	v_mfma_f32_16x16x32_bf16 v[126:129], v[142:145], v[196:199], v[126:129]
	v_mfma_f32_16x16x32_bf16 v[122:125], v[154:157], v[196:199], v[122:125]
	v_mfma_f32_16x16x32_bf16 v[110:113], v[142:145], v[224:227], v[110:113]
	v_mfma_f32_16x16x32_bf16 v[106:109], v[154:157], v[224:227], v[106:109]
	v_mfma_f32_16x16x32_bf16 v[94:97], v[142:145], v[232:235], v[94:97]
	v_mfma_f32_16x16x32_bf16 v[90:93], v[154:157], v[232:235], v[90:93]
	v_mfma_f32_16x16x32_bf16 v[78:81], v[142:145], v[240:243], v[78:81]
	v_mfma_f32_16x16x32_bf16 v[74:77], v[154:157], v[240:243], v[74:77]
	v_mfma_f32_16x16x32_bf16 v[126:129], v[146:149], v[220:223], v[126:129]
	v_mfma_f32_16x16x32_bf16 v[122:125], v[158:161], v[220:223], v[122:125]
	v_mfma_f32_16x16x32_bf16 v[110:113], v[146:149], v[228:231], v[110:113]
	v_mfma_f32_16x16x32_bf16 v[106:109], v[158:161], v[228:231], v[106:109]
	v_mfma_f32_16x16x32_bf16 v[94:97], v[146:149], v[236:239], v[94:97]
	v_mfma_f32_16x16x32_bf16 v[90:93], v[158:161], v[236:239], v[90:93]
	v_mfma_f32_16x16x32_bf16 v[78:81], v[146:149], v[244:247], v[78:81]
	v_mfma_f32_16x16x32_bf16 v[74:77], v[158:161], v[244:247], v[74:77]
	s_setprio 0
	s_setprio 1
	v_mfma_f32_16x16x32_bf16 v[118:121], v[180:183], v[196:199], v[118:121]
	v_mfma_f32_16x16x32_bf16 v[114:117], v[188:191], v[196:199], v[114:117]
	v_mfma_f32_16x16x32_bf16 v[102:105], v[180:183], v[224:227], v[102:105]
	v_mfma_f32_16x16x32_bf16 v[98:101], v[188:191], v[224:227], v[98:101]
	v_mfma_f32_16x16x32_bf16 v[86:89], v[180:183], v[232:235], v[86:89]
	v_mfma_f32_16x16x32_bf16 v[82:85], v[188:191], v[232:235], v[82:85]
	v_mfma_f32_16x16x32_bf16 v[70:73], v[180:183], v[240:243], v[70:73]
	v_mfma_f32_16x16x32_bf16 v[66:69], v[188:191], v[240:243], v[66:69]
	v_mfma_f32_16x16x32_bf16 v[118:121], v[184:187], v[220:223], v[118:121]
	v_mfma_f32_16x16x32_bf16 v[114:117], v[192:195], v[220:223], v[114:117]
	v_mfma_f32_16x16x32_bf16 v[102:105], v[184:187], v[228:231], v[102:105]
	v_mfma_f32_16x16x32_bf16 v[98:101], v[192:195], v[228:231], v[98:101]
	v_mfma_f32_16x16x32_bf16 v[86:89], v[184:187], v[236:239], v[86:89]
	v_mfma_f32_16x16x32_bf16 v[82:85], v[192:195], v[236:239], v[82:85]
	v_mfma_f32_16x16x32_bf16 v[70:73], v[184:187], v[244:247], v[70:73]
	v_mfma_f32_16x16x32_bf16 v[66:69], v[192:195], v[244:247], v[66:69]
	s_setprio 0
	s_barrier
; #define PG8_STAGE(bufoff, gbase, voff) do { _Pragma("unroll") for (int _i = 0; _i < 2; ++_i) \
;         __builtin_amdgcn_global_load_lds((const unsigned*)((const char*)(gbase) + (voff)[_i]), (PG8_LAS unsigned*)(lds + (bufoff) + ldsw + _i * 8192), 16, 0, 0); } while (0)
; #define PG8_WAIT_V(n) asm volatile("s_waitcnt vmcnt(" #n ")" ::: "memory")
; #define PG8_WAIT_L(n) asm volatile("s_waitcnt lgkmcnt(" #n ")" ::: "memory")
; #define PG8_BAR __builtin_amdgcn_s_barrier()
; #define PG8_SCHED __builtin_amdgcn_sched_barrier(0)
; template <class Epi, class Sched, bool ALIGN_EPI = false, bool SP2 = false, bool FP8 = false>
; __device__ __forceinline__ void gemm_phase(PG8_LAS unsigned char* lds, const Gemm g, const Sched& S, const Epi& E, const int tid) {
;     ...
;         for (int t = 0; t < nt; t += 2) {
;             const bool last = (t == nt - 2);
;             const char* a1 = cA + (size_t)(t + 1) * kstep;
;             const char* a2 = last ? nA : cA + (size_t)(t + 2) * kstep; const char* b2 = last ? nB : cB + (size_t)(t + 2) * kstep;
;             const char* a3 = a2 + kstep; const char* b3 = b2 + kstep;
;             if (last && has_next) S.a_ready(nxt);
;     ...
;             PG8_WAIT_V(8); PG8_WAIT_L(0); PG8_BAR; PG8_MMA(0, 0, At, B0); PG8_MMA(0, 1, At, B1); PG8_BAR; PG8_SCHED;
;             PG8_LDA(At, 1, 1); PG8_STAGE(PG8_SB(1, 0), b3, voffB); PG8_STAGE(PG8_SB(1, 1), b3 + hstepB, voffB); PG8_STAGE(PG8_SA(1, 0), a3, voffA);
;             PG8_WAIT_V(8); PG8_WAIT_L(0); PG8_BAR; PG8_MMA(1, 0, At, B0); PG8_MMA(1, 1, At, B1); PG8_BAR; PG8_SCHED;
	s_add_i32 s40, s57, s42
	v_lshl_add_u64 v[166:167], v[200:201], 0, s[38:39]
	s_mov_b32 m0, s40
	ds_read_b128 v[196:199], v152 offset:49152
	ds_read_b128 v[220:223], v152 offset:50176
	ds_read_b128 v[224:227], v152 offset:51200
	ds_read_b128 v[228:231], v152 offset:52224
	ds_read_b128 v[232:235], v152 offset:53248
	ds_read_b128 v[236:239], v152 offset:54272
	ds_read_b128 v[240:243], v152 offset:55296
	ds_read_b128 v[244:247], v152 offset:56320
	global_load_lds_dwordx4 v[166:167], off
	s_add_i32 m0, s40, 0x2000
	s_add_u32 s36, s36, 0x80080
	v_lshl_add_u64 v[166:167], v[248:249], 0, s[38:39]
	s_addc_u32 s37, s37, 0
	s_add_i32 s40, s58, s42
	global_load_lds_dwordx4 v[166:167], off
	v_lshl_add_u64 v[166:167], s[36:37], 0, v[134:135]
	s_mov_b32 m0, s40
	v_lshl_add_u64 v[164:165], v[164:165], 0, s[38:39]
	global_load_lds_dwordx4 v[166:167], off
	v_lshl_add_u64 v[166:167], s[36:37], 0, v[130:131]
	s_add_i32 m0, s40, 0x2000
	s_nop 0
	global_load_lds_dwordx4 v[166:167], off
	v_lshl_add_u64 v[166:167], v[250:251], 0, s[38:39]
	s_mov_b32 m0, s47
	s_nop 0
	global_load_lds_dwordx4 v[166:167], off
	s_mov_b32 m0, s48
	s_nop 0
	global_load_lds_dwordx4 v[164:165], off
	s_waitcnt vmcnt(8)
	s_waitcnt lgkmcnt(0)
	s_barrier
	s_setprio 1
	s_waitcnt lgkmcnt(0)
	v_mfma_f32_16x16x32_bf16 v[62:65], v[142:145], v[196:199], v[62:65]
	v_mfma_f32_16x16x32_bf16 v[58:61], v[154:157], v[196:199], v[58:61]
	v_mfma_f32_16x16x32_bf16 v[46:49], v[142:145], v[224:227], v[46:49]
	v_mfma_f32_16x16x32_bf16 v[42:45], v[154:157], v[224:227], v[42:45]
	v_mfma_f32_16x16x32_bf16 v[28:31], v[142:145], v[232:235], v[28:31]
	v_mfma_f32_16x16x32_bf16 v[24:27], v[154:157], v[232:235], v[24:27]
	v_mfma_f32_16x16x32_bf16 v[12:15], v[142:145], v[240:243], v[12:15]
	v_mfma_f32_16x16x32_bf16 v[8:11], v[154:157], v[240:243], v[8:11]
	v_mfma_f32_16x16x32_bf16 v[62:65], v[146:149], v[220:223], v[62:65]
	v_mfma_f32_16x16x32_bf16 v[58:61], v[158:161], v[220:223], v[58:61]
	v_mfma_f32_16x16x32_bf16 v[46:49], v[146:149], v[228:231], v[46:49]
	v_mfma_f32_16x16x32_bf16 v[42:45], v[158:161], v[228:231], v[42:45]
	v_mfma_f32_16x16x32_bf16 v[28:31], v[146:149], v[236:239], v[28:31]
	v_mfma_f32_16x16x32_bf16 v[24:27], v[158:161], v[236:239], v[24:27]
	v_mfma_f32_16x16x32_bf16 v[12:15], v[146:149], v[244:247], v[12:15]
	v_mfma_f32_16x16x32_bf16 v[8:11], v[158:161], v[244:247], v[8:11]
	s_setprio 0
	s_setprio 1
	v_mfma_f32_16x16x32_bf16 v[54:57], v[180:183], v[196:199], v[54:57]
	v_mfma_f32_16x16x32_bf16 v[50:53], v[188:191], v[196:199], v[50:53]
	v_mfma_f32_16x16x32_bf16 v[38:41], v[180:183], v[224:227], v[38:41]
	v_mfma_f32_16x16x32_bf16 v[34:37], v[188:191], v[224:227], v[34:37]
	v_mfma_f32_16x16x32_bf16 v[20:23], v[180:183], v[232:235], v[20:23]
	v_mfma_f32_16x16x32_bf16 v[16:19], v[188:191], v[232:235], v[16:19]
	v_mfma_f32_16x16x32_bf16 v[4:7], v[180:183], v[240:243], v[4:7]
	v_mfma_f32_16x16x32_bf16 v[0:3], v[188:191], v[240:243], v[0:3]
	v_mfma_f32_16x16x32_bf16 v[54:57], v[184:187], v[220:223], v[54:57]
	v_mfma_f32_16x16x32_bf16 v[50:53], v[192:195], v[220:223], v[50:53]
	v_mfma_f32_16x16x32_bf16 v[38:41], v[184:187], v[228:231], v[38:41]
	v_mfma_f32_16x16x32_bf16 v[34:37], v[192:195], v[228:231], v[34:37]
	v_mfma_f32_16x16x32_bf16 v[20:23], v[184:187], v[236:239], v[20:23]
	v_mfma_f32_16x16x32_bf16 v[16:19], v[192:195], v[236:239], v[16:19]
	v_mfma_f32_16x16x32_bf16 v[4:7], v[184:187], v[244:247], v[4:7]
	v_mfma_f32_16x16x32_bf16 v[0:3], v[192:195], v[244:247], v[0:3]
	s_setprio 0
	s_add_i32 s56, s56, 2
	s_add_u32 s34, s34, 0x100
	s_addc_u32 s35, s35, 0
	s_add_u32 s54, s54, 0x100
	s_addc_u32 s55, s55, 0
	s_add_u32 s36, s34, 0xfff80080
	s_addc_u32 s37, s35, -1
	s_add_i32 s57, 0, 0x10000
	s_cmp_eq_u32 s56, 28
	s_cselect_b32 s41, s27, s37
	s_cselect_b32 s40, s52, s36
	v_add_u32_e32 v153, s57, v150
	s_cselect_b32 s37, s25, s55
	s_cselect_b32 s36, s53, s54
	s_add_i32 s60, 0, 0x14000
	s_cmp_gt_u32 s56, 29
	s_barrier
	s_cbranch_scc0 .Lrot_98
	v_lshl_add_u32 v142, s51, 8, v33
	v_ashrrev_i32_e32 v143, 31, v142
	v_lshl_add_u64 v[148:149], v[142:143], 3, s[8:9]
	global_load_dwordx2 v[220:221], v[148:149], off
	global_load_dwordx2 v[222:223], v[148:149], off offset:128
	global_load_dwordx2 v[224:225], v[148:149], off offset:256
	global_load_dwordx2 v[226:227], v[148:149], off offset:384
	global_load_dwordx2 v[228:229], v[148:149], off offset:1024
	global_load_dwordx2 v[230:231], v[148:149], off offset:1152
	global_load_dwordx2 v[232:233], v[148:149], off offset:1280
	global_load_dwordx2 v[234:235], v[148:149], off offset:1408
	s_and_b64 vcc, exec, s[16:17]
	s_cbranch_vccz .LBB0_101
	s_barrier

; #define PG8_STAGE(bufoff, gbase, voff) do { _Pragma("unroll") for (int _i = 0; _i < 2; ++_i) \
;         __builtin_amdgcn_global_load_lds((const unsigned*)((const char*)(gbase) + (voff)[_i]), (PG8_LAS unsigned*)(lds + (bufoff) + ldsw + _i * 8192), 16, 0, 0); } while (0)
; #define PG8_WAIT_V(n) asm volatile("s_waitcnt vmcnt(" #n ")" ::: "memory")
; #define PG8_WAIT_L(n) asm volatile("s_waitcnt lgkmcnt(" #n ")" ::: "memory")
; #define PG8_BAR __builtin_amdgcn_s_barrier()
; #define PG8_SCHED __builtin_amdgcn_sched_barrier(0)
; template <class Epi, class Sched, bool ALIGN_EPI = false, bool SP2 = false, bool FP8 = false>
; __device__ __forceinline__ void gemm_phase(PG8_LAS unsigned char* lds, const Gemm g, const Sched& S, const Epi& E, const int tid) {
;     ...
;             PG8_LDB(B0, 0, 0); PG8_LDB(B1, 0, 1); PG8_SCHED; PG8_LDA(At, 0, 0); PG8_STAGE(PG8_SA(1, 1), a1 + hstepA, voffA);
;             PG8_WAIT_V(8); PG8_WAIT_L(0); PG8_BAR; PG8_MMA(0, 0, At, B0); PG8_MMA(0, 1, At, B1); PG8_BAR; PG8_SCHED;
.Lrot_114:
	ds_read_b128 v[16:19], v0
	ds_read_b128 v[20:23], v0 offset:1024
	ds_read_b128 v[24:27], v0 offset:2048
	ds_read_b128 v[28:31], v0 offset:3072
	ds_read_b128 v[0:3], v12
	ds_read_b128 v[4:7], v12 offset:1024
	ds_read_b128 v[8:11], v12 offset:2048
	ds_read_b128 v[12:15], v12 offset:3072
	v_lshl_add_u64 v[164:165], s[30:31], 0, v[188:189]
	s_add_i32 m0, s45, 0xc000
	ds_read_b128 v[192:195], v200
	ds_read_b128 v[196:199], v200 offset:1024
	ds_read_b128 v[220:223], v200 offset:2048
	ds_read_b128 v[224:227], v200 offset:3072
	ds_read_b128 v[228:231], v200 offset:4096
	ds_read_b128 v[232:235], v200 offset:5120
	ds_read_b128 v[236:239], v200 offset:6144
	ds_read_b128 v[240:243], v200 offset:7168
	global_load_lds_dwordx4 v[164:165], off
	v_lshl_add_u64 v[164:165], s[30:31], 0, v[190:191]
	s_add_i32 m0, s45, 0xe000
	s_nop 0
	global_load_lds_dwordx4 v[164:165], off
	s_cmp_eq_i32 s54, -2
	s_cbranch_scc1 .Lskw_1_0
	s_waitcnt vmcnt(8)

; #define PG8_STAGE(bufoff, gbase, voff) do { _Pragma("unroll") for (int _i = 0; _i < 2; ++_i) \
;         __builtin_amdgcn_global_load_lds((const unsigned*)((const char*)(gbase) + (voff)[_i]), (PG8_LAS unsigned*)(lds + (bufoff) + ldsw + _i * 8192), 16, 0, 0); } while (0)
; #define PG8_WAIT_V(n) asm volatile("s_waitcnt vmcnt(" #n ")" ::: "memory")
; #define PG8_WAIT_L(n) asm volatile("s_waitcnt lgkmcnt(" #n ")" ::: "memory")
; #define PG8_BAR __builtin_amdgcn_s_barrier()
; #define PG8_SCHED __builtin_amdgcn_sched_barrier(0)
; template <class Epi, class Sched, bool ALIGN_EPI = false, bool SP2 = false, bool FP8 = false>
; __device__ __forceinline__ void gemm_phase(PG8_LAS unsigned char* lds, const Gemm g, const Sched& S, const Epi& E, const int tid) {
;     ...
;             PG8_WAIT_V(8); PG8_WAIT_L(0); PG8_BAR; PG8_MMA(0, 0, At, B0); PG8_MMA(0, 1, At, B1); PG8_BAR; PG8_SCHED;
;             PG8_LDA(At, 0, 1); PG8_STAGE(PG8_SB(0, 0), b2, voffB); PG8_STAGE(PG8_SB(0, 1), b2 + hstepB, voffB); PG8_STAGE(PG8_SA(0, 0), a2, voffA);
;             PG8_WAIT_V(8); PG8_WAIT_L(0); PG8_BAR; PG8_MMA(1, 0, At, B0); PG8_MMA(1, 1, At, B1); PG8_BAR; PG8_SCHED;
;             PG8_LDB(B0, 1, 0); PG8_LDB(B1, 1, 1); PG8_SCHED; PG8_LDA(At, 1, 0); PG8_STAGE(PG8_SA(0, 1), a2 + hstepA, voffA);
;             PG8_WAIT_V(8); PG8_WAIT_L(0); PG8_BAR; PG8_MMA(0, 0, At, B0); PG8_MMA(0, 1, At, B1); PG8_BAR; PG8_SCHED;
.Lskw_1_1:
	s_waitcnt lgkmcnt(0)
	s_barrier
	s_setprio 1
	s_waitcnt lgkmcnt(0)
	v_mfma_f32_16x16x128_f8f6f4 v[94:97], v[16:23], v[220:227], v[94:97]
	v_mfma_f32_16x16x128_f8f6f4 v[90:93], v[24:31], v[220:227], v[90:93]
	v_mfma_f32_16x16x128_f8f6f4 v[78:81], v[16:23], v[228:235], v[78:81]
	v_mfma_f32_16x16x128_f8f6f4 v[74:77], v[24:31], v[228:235], v[74:77]
	v_mfma_f32_16x16x128_f8f6f4 v[62:65], v[16:23], v[236:243], v[62:65]
	v_mfma_f32_16x16x128_f8f6f4 v[58:61], v[24:31], v[236:243], v[58:61]
	v_mfma_f32_16x16x128_f8f6f4 v[46:49], v[16:23], v[244:251], v[46:49]
	v_mfma_f32_16x16x128_f8f6f4 v[42:45], v[24:31], v[244:251], v[42:45]
	s_setprio 0
	s_setprio 1
	v_mfma_f32_16x16x128_f8f6f4 v[86:89], v[0:7], v[220:227], v[86:89]
	v_mfma_f32_16x16x128_f8f6f4 v[82:85], v[8:15], v[220:227], v[82:85]
	v_mfma_f32_16x16x128_f8f6f4 v[70:73], v[0:7], v[228:235], v[70:73]
	v_mfma_f32_16x16x128_f8f6f4 v[66:69], v[8:15], v[228:235], v[66:69]
	v_mfma_f32_16x16x128_f8f6f4 v[54:57], v[0:7], v[236:243], v[54:57]
	v_mfma_f32_16x16x128_f8f6f4 v[50:53], v[8:15], v[236:243], v[50:53]
	v_mfma_f32_16x16x128_f8f6f4 v[38:41], v[0:7], v[244:251], v[38:41]
	v_mfma_f32_16x16x128_f8f6f4 v[34:37], v[8:15], v[244:251], v[34:37]
	s_setprio 0
	s_barrier
	s_add_i32 s55, 0, 0x18000
	s_add_i32 s56, 0, 0x1c000
	v_add_u32_e32 v12, s55, v163
	v_add_u32_e32 v28, s56, v163
	ds_read_b128 v[0:3], v12
	ds_read_b128 v[4:7], v12 offset:1024
	ds_read_b128 v[8:11], v12 offset:2048
	ds_read_b128 v[12:15], v12 offset:3072
	ds_read_b128 v[16:19], v28
	ds_read_b128 v[20:23], v28 offset:1024
	ds_read_b128 v[24:27], v28 offset:2048
	ds_read_b128 v[28:31], v28 offset:3072
	s_add_u32 s36, s36, 0x40000
	s_addc_u32 s37, s37, 0
	s_mov_b32 m0, s47
	v_lshl_add_u64 v[164:165], s[36:37], 0, v[186:187]
	ds_read_b128 v[220:223], v200 offset:32768
	ds_read_b128 v[224:227], v200 offset:33792
	ds_read_b128 v[228:231], v200 offset:34816
	ds_read_b128 v[232:235], v200 offset:35840
	ds_read_b128 v[236:239], v200 offset:36864
	ds_read_b128 v[240:243], v200 offset:37888
	ds_read_b128 v[244:247], v200 offset:38912
	ds_read_b128 v[248:251], v200 offset:39936
	global_load_lds_dwordx4 v[164:165], off
	v_lshl_add_u64 v[164:165], s[36:37], 0, v[182:183]
	s_mov_b32 m0, s48
	s_nop 0
	global_load_lds_dwordx4 v[164:165], off
	s_waitcnt vmcnt(8)
	s_waitcnt lgkmcnt(0)
	s_barrier
	s_setprio 1
	s_waitcnt lgkmcnt(0)
	v_mfma_f32_16x16x128_f8f6f4 v[158:161], v[0:7], v[220:227], v[158:161]
	v_mfma_f32_16x16x128_f8f6f4 v[154:157], v[8:15], v[220:227], v[154:157]
	v_mfma_f32_16x16x128_f8f6f4 v[142:145], v[0:7], v[228:235], v[142:145]
	v_mfma_f32_16x16x128_f8f6f4 v[138:141], v[8:15], v[228:235], v[138:141]
	v_mfma_f32_16x16x128_f8f6f4 v[126:129], v[0:7], v[236:243], v[126:129]
	v_mfma_f32_16x16x128_f8f6f4 v[122:125], v[8:15], v[236:243], v[122:125]
	v_mfma_f32_16x16x128_f8f6f4 v[110:113], v[0:7], v[244:251], v[110:113]
	v_mfma_f32_16x16x128_f8f6f4 v[106:109], v[8:15], v[244:251], v[106:109]
	s_setprio 0
	s_setprio 1
	v_mfma_f32_16x16x128_f8f6f4 v[150:153], v[16:23], v[220:227], v[150:153]
	v_mfma_f32_16x16x128_f8f6f4 v[146:149], v[24:31], v[220:227], v[146:149]
	v_mfma_f32_16x16x128_f8f6f4 v[134:137], v[16:23], v[228:235], v[134:137]
	v_mfma_f32_16x16x128_f8f6f4 v[130:133], v[24:31], v[228:235], v[130:133]
	v_mfma_f32_16x16x128_f8f6f4 v[118:121], v[16:23], v[236:243], v[118:121]
	v_mfma_f32_16x16x128_f8f6f4 v[114:117], v[24:31], v[236:243], v[114:117]
	v_mfma_f32_16x16x128_f8f6f4 v[102:105], v[16:23], v[244:251], v[102:105]
	v_mfma_f32_16x16x128_f8f6f4 v[98:101], v[24:31], v[244:251], v[98:101]
	s_setprio 0
	s_barrier
; #define PG8_STAGE(bufoff, gbase, voff) do { _Pragma("unroll") for (int _i = 0; _i < 2; ++_i) \
;         __builtin_amdgcn_global_load_lds((const unsigned*)((const char*)(gbase) + (voff)[_i]), (PG8_LAS unsigned*)(lds + (bufoff) + ldsw + _i * 8192), 16, 0, 0); } while (0)
; #define PG8_WAIT_V(n) asm volatile("s_waitcnt vmcnt(" #n ")" ::: "memory")
; #define PG8_WAIT_L(n) asm volatile("s_waitcnt lgkmcnt(" #n ")" ::: "memory")
; #define PG8_BAR __builtin_amdgcn_s_barrier()
; #define PG8_SCHED __builtin_amdgcn_sched_barrier(0)
; template <class Epi, class Sched, bool ALIGN_EPI = false, bool SP2 = false, bool FP8 = false>
; __device__ __forceinline__ void gemm_phase(PG8_LAS unsigned char* lds, const Gemm g, const Sched& S, const Epi& E, const int tid) {
;     ...
;         for (int t = 0; t < nt; t += 2) {
;             const bool last = (t == nt - 2);
;             const char* a1 = cA + (size_t)(t + 1) * kstep;
;             const char* a2 = last ? nA : cA + (size_t)(t + 2) * kstep; const char* b2 = last ? nB : cB + (size_t)(t + 2) * kstep;
;             const char* a3 = a2 + kstep; const char* b3 = b2 + kstep;
;             if (last && has_next) S.a_ready(nxt);
;     ...
;             PG8_WAIT_V(8); PG8_WAIT_L(0); PG8_BAR; PG8_MMA(0, 0, At, B0); PG8_MMA(0, 1, At, B1); PG8_BAR; PG8_SCHED;
;             PG8_LDA(At, 1, 1); PG8_STAGE(PG8_SB(1, 0), b3, voffB); PG8_STAGE(PG8_SB(1, 1), b3 + hstepB, voffB); PG8_STAGE(PG8_SA(1, 0), a3, voffA);
;             PG8_WAIT_V(8); PG8_WAIT_L(0); PG8_BAR; PG8_MMA(1, 0, At, B0); PG8_MMA(1, 1, At, B1); PG8_BAR; PG8_SCHED;
	s_add_i32 s36, s55, s44
	v_lshl_add_u64 v[164:165], v[192:193], 0, s[38:39]
	s_mov_b32 m0, s36
	ds_read_b128 v[220:223], v200 offset:49152
	ds_read_b128 v[224:227], v200 offset:50176
	ds_read_b128 v[228:231], v200 offset:51200
	ds_read_b128 v[232:235], v200 offset:52224
	ds_read_b128 v[236:239], v200 offset:53248
	ds_read_b128 v[240:243], v200 offset:54272
	ds_read_b128 v[244:247], v200 offset:55296
	ds_read_b128 v[248:251], v200 offset:56320
	global_load_lds_dwordx4 v[164:165], off
	s_add_i32 m0, s36, 0x2000
	s_add_u32 s34, s34, 0x40080
	v_lshl_add_u64 v[164:165], v[194:195], 0, s[38:39]
	s_addc_u32 s35, s35, 0
	s_add_i32 s36, s56, s44
	global_load_lds_dwordx4 v[164:165], off
	v_lshl_add_u64 v[164:165], s[34:35], 0, v[184:185]
	s_mov_b32 m0, s36
	s_nop 0
	global_load_lds_dwordx4 v[164:165], off
	v_lshl_add_u64 v[164:165], s[34:35], 0, v[180:181]
	s_add_i32 m0, s36, 0x2000
	s_nop 0
	global_load_lds_dwordx4 v[164:165], off
	v_lshl_add_u64 v[164:165], v[196:197], 0, s[38:39]
	s_mov_b32 m0, s49
	s_nop 0
	global_load_lds_dwordx4 v[164:165], off
	v_lshl_add_u64 v[164:165], v[198:199], 0, s[38:39]
	s_mov_b32 m0, s50
	s_nop 0
	global_load_lds_dwordx4 v[164:165], off
	s_waitcnt vmcnt(8)
	s_waitcnt lgkmcnt(0)
	s_barrier
	s_setprio 1
	s_waitcnt lgkmcnt(0)
	v_mfma_f32_16x16x128_f8f6f4 v[94:97], v[0:7], v[220:227], v[94:97]
	v_mfma_f32_16x16x128_f8f6f4 v[90:93], v[8:15], v[220:227], v[90:93]
	v_mfma_f32_16x16x128_f8f6f4 v[78:81], v[0:7], v[228:235], v[78:81]
	v_mfma_f32_16x16x128_f8f6f4 v[74:77], v[8:15], v[228:235], v[74:77]
	v_mfma_f32_16x16x128_f8f6f4 v[62:65], v[0:7], v[236:243], v[62:65]
	v_mfma_f32_16x16x128_f8f6f4 v[58:61], v[8:15], v[236:243], v[58:61]
	v_mfma_f32_16x16x128_f8f6f4 v[46:49], v[0:7], v[244:251], v[46:49]
	v_mfma_f32_16x16x128_f8f6f4 v[42:45], v[8:15], v[244:251], v[42:45]
	s_setprio 0
	s_setprio 1
	v_mfma_f32_16x16x128_f8f6f4 v[86:89], v[16:23], v[220:227], v[86:89]
	v_mfma_f32_16x16x128_f8f6f4 v[82:85], v[24:31], v[220:227], v[82:85]
	v_mfma_f32_16x16x128_f8f6f4 v[70:73], v[16:23], v[228:235], v[70:73]
	v_mfma_f32_16x16x128_f8f6f4 v[66:69], v[24:31], v[228:235], v[66:69]
	v_mfma_f32_16x16x128_f8f6f4 v[54:57], v[16:23], v[236:243], v[54:57]
	v_mfma_f32_16x16x128_f8f6f4 v[50:53], v[24:31], v[236:243], v[50:53]
	v_mfma_f32_16x16x128_f8f6f4 v[38:41], v[16:23], v[244:251], v[38:41]
	v_mfma_f32_16x16x128_f8f6f4 v[34:37], v[24:31], v[244:251], v[34:37]
	s_setprio 0
	s_add_i32 s54, s54, 2
	s_add_u32 s30, s30, 0x100
	s_addc_u32 s31, s31, 0
	s_add_u32 s52, s52, 0x100
	s_addc_u32 s53, s53, 0
	s_add_u32 s34, s30, 0xfffc0080
	s_addc_u32 s35, s31, -1
	s_add_i32 s55, 0, 0x10000
	s_cmp_eq_u32 s54, 12
	s_cselect_b32 s37, s22, s35
	s_cselect_b32 s36, s25, s34
	s_cselect_b32 s35, s17, s53
	s_cselect_b32 s34, s33, s52
	s_add_i32 s56, 0, 0x14000
	v_add_u32_e32 v0, s55, v163
	v_add_u32_e32 v12, s56, v163
	s_cmp_gt_u32 s54, 13
	s_barrier
	s_cbranch_scc0 .Lrot_114
	v_lshl_add_u32 v0, s20, 8, v33
	v_ashrrev_i32_e32 v1, 31, v0
	v_lshl_add_u64 v[2:3], v[0:1], 3, s[8:9]
	global_load_dwordx2 v[220:221], v[2:3], off
	global_load_dwordx2 v[222:223], v[2:3], off offset:128
	global_load_dwordx2 v[224:225], v[2:3], off offset:256
	global_load_dwordx2 v[226:227], v[2:3], off offset:384
	global_load_dwordx2 v[228:229], v[2:3], off offset:1024
	global_load_dwordx2 v[230:231], v[2:3], off offset:1152
	global_load_dwordx2 v[232:233], v[2:3], off offset:1280
	global_load_dwordx2 v[234:235], v[2:3], off offset:1408
	s_and_b64 vcc, exec, s[14:15]
	s_cbranch_vccz .LBB0_117
	s_barrier

; #define PG8_STAGE(bufoff, gbase, voff) do { _Pragma("unroll") for (int _i = 0; _i < 2; ++_i) \
;         __builtin_amdgcn_global_load_lds((const unsigned*)((const char*)(gbase) + (voff)[_i]), (PG8_LAS unsigned*)(lds + (bufoff) + ldsw + _i * 8192), 16, 0, 0); } while (0)
; #define PG8_WAIT_V(n) asm volatile("s_waitcnt vmcnt(" #n ")" ::: "memory")
; #define PG8_WAIT_L(n) asm volatile("s_waitcnt lgkmcnt(" #n ")" ::: "memory")
; #define PG8_BAR __builtin_amdgcn_s_barrier()
; #define PG8_SCHED __builtin_amdgcn_sched_barrier(0)
; template <class Epi, class Sched, bool ALIGN_EPI = false, bool SP2 = false, bool FP8 = false>
; __device__ __forceinline__ void gemm_phase(PG8_LAS unsigned char* lds, const Gemm g, const Sched& S, const Epi& E, const int tid) {
;     ...
;             PG8_LDB(B0, 0, 0); PG8_LDB(B1, 0, 1); PG8_SCHED; PG8_LDA(At, 0, 0); PG8_STAGE(PG8_SA(1, 1), a1 + hstepA, voffA);
;             PG8_WAIT_V(8); PG8_WAIT_L(0); PG8_BAR; PG8_MMA(0, 0, At, B0); PG8_MMA(0, 1, At, B1); PG8_BAR; PG8_SCHED;
.Lrot_457:
	ds_read_b128 v[130:133], v142
	ds_read_b128 v[134:137], v142 offset:1024
	ds_read_b128 v[138:141], v142 offset:2048
	ds_read_b128 v[142:145], v142 offset:3072
	ds_read_b128 v[146:149], v158
	ds_read_b128 v[150:153], v158 offset:1024
	ds_read_b128 v[154:157], v158 offset:2048
	ds_read_b128 v[158:161], v158 offset:3072
	v_lshl_add_u64 v[164:165], s[8:9], 0, v[188:189]
	s_add_i32 m0, s46, 0xc000
	ds_read_b128 v[192:195], v198
	ds_read_b128 v[220:223], v198 offset:1024
	ds_read_b128 v[224:227], v198 offset:2048
	ds_read_b128 v[228:231], v198 offset:3072
	ds_read_b128 v[232:235], v198 offset:4096
	ds_read_b128 v[236:239], v198 offset:5120
	ds_read_b128 v[240:243], v198 offset:6144
	ds_read_b128 v[244:247], v198 offset:7168
	global_load_lds_dwordx4 v[164:165], off
	v_lshl_add_u64 v[164:165], s[8:9], 0, v[190:191]
	s_add_i32 m0, s46, 0xe000
	s_nop 0
	global_load_lds_dwordx4 v[164:165], off
	s_cmp_eq_i32 s60, 2
	s_cbranch_scc1 .Lskw_2_0
	s_waitcnt vmcnt(8)

; #define PG8_STAGE(bufoff, gbase, voff) do { _Pragma("unroll") for (int _i = 0; _i < 2; ++_i) \
;         __builtin_amdgcn_global_load_lds((const unsigned*)((const char*)(gbase) + (voff)[_i]), (PG8_LAS unsigned*)(lds + (bufoff) + ldsw + _i * 8192), 16, 0, 0); } while (0)
; #define PG8_WAIT_V(n) asm volatile("s_waitcnt vmcnt(" #n ")" ::: "memory")
; #define PG8_WAIT_L(n) asm volatile("s_waitcnt lgkmcnt(" #n ")" ::: "memory")
; #define PG8_BAR __builtin_amdgcn_s_barrier()
; #define PG8_SCHED __builtin_amdgcn_sched_barrier(0)
; template <class Epi, class Sched, bool ALIGN_EPI = false, bool SP2 = false, bool FP8 = false>
; __device__ __forceinline__ void gemm_phase(PG8_LAS unsigned char* lds, const Gemm g, const Sched& S, const Epi& E, const int tid) {
;     ...
;             PG8_WAIT_V(8); PG8_WAIT_L(0); PG8_BAR; PG8_MMA(0, 0, At, B0); PG8_MMA(0, 1, At, B1); PG8_BAR; PG8_SCHED;
;             PG8_LDA(At, 0, 1); PG8_STAGE(PG8_SB(0, 0), b2, voffB); PG8_STAGE(PG8_SB(0, 1), b2 + hstepB, voffB); PG8_STAGE(PG8_SA(0, 0), a2, voffA);
;             PG8_WAIT_V(8); PG8_WAIT_L(0); PG8_BAR; PG8_MMA(1, 0, At, B0); PG8_MMA(1, 1, At, B1); PG8_BAR; PG8_SCHED;
;             PG8_LDB(B0, 1, 0); PG8_LDB(B1, 1, 1); PG8_SCHED; PG8_LDA(At, 1, 0); PG8_STAGE(PG8_SA(0, 1), a2 + hstepA, voffA);
;             PG8_WAIT_V(8); PG8_WAIT_L(0); PG8_BAR; PG8_MMA(0, 0, At, B0); PG8_MMA(0, 1, At, B1); PG8_BAR; PG8_SCHED;
.Lskw_2_1:
	s_waitcnt lgkmcnt(0)
	s_barrier
	s_setprio 1
	s_waitcnt lgkmcnt(0)
	v_mfma_f32_16x16x32_bf16 v[62:65], v[130:133], v[192:195], v[62:65]
	v_mfma_f32_16x16x32_bf16 v[58:61], v[138:141], v[192:195], v[58:61]
	v_mfma_f32_16x16x32_bf16 v[54:57], v[130:133], v[224:227], v[54:57]
	v_mfma_f32_16x16x32_bf16 v[50:53], v[138:141], v[224:227], v[50:53]
	v_mfma_f32_16x16x32_bf16 v[46:49], v[130:133], v[232:235], v[46:49]
	v_mfma_f32_16x16x32_bf16 v[42:45], v[138:141], v[232:235], v[42:45]
	v_mfma_f32_16x16x32_bf16 v[38:41], v[130:133], v[240:243], v[38:41]
	v_mfma_f32_16x16x32_bf16 v[34:37], v[138:141], v[240:243], v[34:37]
	v_mfma_f32_16x16x32_bf16 v[62:65], v[134:137], v[220:223], v[62:65]
	v_mfma_f32_16x16x32_bf16 v[58:61], v[142:145], v[220:223], v[58:61]
	v_mfma_f32_16x16x32_bf16 v[54:57], v[134:137], v[228:231], v[54:57]
	v_mfma_f32_16x16x32_bf16 v[50:53], v[142:145], v[228:231], v[50:53]
	v_mfma_f32_16x16x32_bf16 v[46:49], v[134:137], v[236:239], v[46:49]
	v_mfma_f32_16x16x32_bf16 v[42:45], v[142:145], v[236:239], v[42:45]
	v_mfma_f32_16x16x32_bf16 v[38:41], v[134:137], v[244:247], v[38:41]
	v_mfma_f32_16x16x32_bf16 v[34:37], v[142:145], v[244:247], v[34:37]
	s_setprio 0
	s_setprio 1
	v_mfma_f32_16x16x32_bf16 v[28:31], v[146:149], v[192:195], v[28:31]
	v_mfma_f32_16x16x32_bf16 v[24:27], v[154:157], v[192:195], v[24:27]
	v_mfma_f32_16x16x32_bf16 v[20:23], v[146:149], v[224:227], v[20:23]
	v_mfma_f32_16x16x32_bf16 v[16:19], v[154:157], v[224:227], v[16:19]
	v_mfma_f32_16x16x32_bf16 v[12:15], v[146:149], v[232:235], v[12:15]
	v_mfma_f32_16x16x32_bf16 v[8:11], v[154:157], v[232:235], v[8:11]
	v_mfma_f32_16x16x32_bf16 v[4:7], v[146:149], v[240:243], v[4:7]
	v_mfma_f32_16x16x32_bf16 v[0:3], v[154:157], v[240:243], v[0:3]
	v_mfma_f32_16x16x32_bf16 v[28:31], v[150:153], v[220:223], v[28:31]
	v_mfma_f32_16x16x32_bf16 v[24:27], v[158:161], v[220:223], v[24:27]
	v_mfma_f32_16x16x32_bf16 v[20:23], v[150:153], v[228:231], v[20:23]
	v_mfma_f32_16x16x32_bf16 v[16:19], v[158:161], v[228:231], v[16:19]
	v_mfma_f32_16x16x32_bf16 v[12:15], v[150:153], v[236:239], v[12:15]
	v_mfma_f32_16x16x32_bf16 v[8:11], v[158:161], v[236:239], v[8:11]
	v_mfma_f32_16x16x32_bf16 v[4:7], v[150:153], v[244:247], v[4:7]
	v_mfma_f32_16x16x32_bf16 v[0:3], v[158:161], v[244:247], v[0:3]
	s_setprio 0
	s_barrier
	s_add_i32 s61, 0, 0x18000
	s_add_i32 s62, 0, 0x1c000
	v_add_u32_e32 v142, s61, v163
	v_add_u32_e32 v158, s62, v163
	ds_read_b128 v[130:133], v142
	ds_read_b128 v[134:137], v142 offset:1024
	ds_read_b128 v[138:141], v142 offset:2048
	ds_read_b128 v[142:145], v142 offset:3072
	ds_read_b128 v[146:149], v158
	ds_read_b128 v[150:153], v158 offset:1024
	ds_read_b128 v[154:157], v158 offset:2048
	ds_read_b128 v[158:161], v158 offset:3072
	s_add_u32 s8, s36, 0x3c0000
	s_addc_u32 s9, s37, 0
	s_mov_b32 m0, s48
	v_lshl_add_u64 v[248:249], s[8:9], 0, v[186:187]
	ds_read_b128 v[192:195], v198 offset:32768
	ds_read_b128 v[220:223], v198 offset:33792
	ds_read_b128 v[224:227], v198 offset:34816
	ds_read_b128 v[228:231], v198 offset:35840
	ds_read_b128 v[232:235], v198 offset:36864
	ds_read_b128 v[236:239], v198 offset:37888
	ds_read_b128 v[240:243], v198 offset:38912
	ds_read_b128 v[244:247], v198 offset:39936
	global_load_lds_dwordx4 v[248:249], off
	v_lshl_add_u64 v[248:249], s[8:9], 0, v[182:183]
	s_mov_b32 m0, s49
	s_nop 0
	global_load_lds_dwordx4 v[248:249], off
	s_waitcnt vmcnt(8)
	s_waitcnt lgkmcnt(0)
	s_barrier
	s_setprio 1
	s_waitcnt lgkmcnt(0)
	v_mfma_f32_16x16x32_bf16 v[126:129], v[130:133], v[192:195], v[126:129]
	v_mfma_f32_16x16x32_bf16 v[122:125], v[138:141], v[192:195], v[122:125]
	v_mfma_f32_16x16x32_bf16 v[118:121], v[130:133], v[224:227], v[118:121]
	v_mfma_f32_16x16x32_bf16 v[114:117], v[138:141], v[224:227], v[114:117]
	v_mfma_f32_16x16x32_bf16 v[110:113], v[130:133], v[232:235], v[110:113]
	v_mfma_f32_16x16x32_bf16 v[106:109], v[138:141], v[232:235], v[106:109]
	v_mfma_f32_16x16x32_bf16 v[102:105], v[130:133], v[240:243], v[102:105]
	v_mfma_f32_16x16x32_bf16 v[98:101], v[138:141], v[240:243], v[98:101]
	v_mfma_f32_16x16x32_bf16 v[126:129], v[134:137], v[220:223], v[126:129]
	v_mfma_f32_16x16x32_bf16 v[122:125], v[142:145], v[220:223], v[122:125]
	v_mfma_f32_16x16x32_bf16 v[118:121], v[134:137], v[228:231], v[118:121]
	v_mfma_f32_16x16x32_bf16 v[114:117], v[142:145], v[228:231], v[114:117]
	v_mfma_f32_16x16x32_bf16 v[110:113], v[134:137], v[236:239], v[110:113]
	v_mfma_f32_16x16x32_bf16 v[106:109], v[142:145], v[236:239], v[106:109]
	v_mfma_f32_16x16x32_bf16 v[102:105], v[134:137], v[244:247], v[102:105]
	v_mfma_f32_16x16x32_bf16 v[98:101], v[142:145], v[244:247], v[98:101]
	s_setprio 0
	s_setprio 1
	v_mfma_f32_16x16x32_bf16 v[94:97], v[146:149], v[192:195], v[94:97]
	v_mfma_f32_16x16x32_bf16 v[90:93], v[154:157], v[192:195], v[90:93]
	v_mfma_f32_16x16x32_bf16 v[86:89], v[146:149], v[224:227], v[86:89]
	v_mfma_f32_16x16x32_bf16 v[82:85], v[154:157], v[224:227], v[82:85]
	v_mfma_f32_16x16x32_bf16 v[78:81], v[146:149], v[232:235], v[78:81]
	v_mfma_f32_16x16x32_bf16 v[74:77], v[154:157], v[232:235], v[74:77]
	v_mfma_f32_16x16x32_bf16 v[70:73], v[146:149], v[240:243], v[70:73]
	v_mfma_f32_16x16x32_bf16 v[66:69], v[154:157], v[240:243], v[66:69]
	v_mfma_f32_16x16x32_bf16 v[94:97], v[150:153], v[220:223], v[94:97]
	v_mfma_f32_16x16x32_bf16 v[90:93], v[158:161], v[220:223], v[90:93]
	v_mfma_f32_16x16x32_bf16 v[86:89], v[150:153], v[228:231], v[86:89]
	v_mfma_f32_16x16x32_bf16 v[82:85], v[158:161], v[228:231], v[82:85]
	v_mfma_f32_16x16x32_bf16 v[78:81], v[150:153], v[236:239], v[78:81]
	v_mfma_f32_16x16x32_bf16 v[74:77], v[158:161], v[236:239], v[74:77]
	v_mfma_f32_16x16x32_bf16 v[70:73], v[150:153], v[244:247], v[70:73]
	v_mfma_f32_16x16x32_bf16 v[66:69], v[158:161], v[244:247], v[66:69]
	s_setprio 0
	s_barrier
; #define PG8_STAGE(bufoff, gbase, voff) do { _Pragma("unroll") for (int _i = 0; _i < 2; ++_i) \
;         __builtin_amdgcn_global_load_lds((const unsigned*)((const char*)(gbase) + (voff)[_i]), (PG8_LAS unsigned*)(lds + (bufoff) + ldsw + _i * 8192), 16, 0, 0); } while (0)
; #define PG8_WAIT_V(n) asm volatile("s_waitcnt vmcnt(" #n ")" ::: "memory")
; #define PG8_WAIT_L(n) asm volatile("s_waitcnt lgkmcnt(" #n ")" ::: "memory")
; #define PG8_BAR __builtin_amdgcn_s_barrier()
; #define PG8_SCHED __builtin_amdgcn_sched_barrier(0)
; template <class Epi, class Sched, bool ALIGN_EPI = false, bool SP2 = false, bool FP8 = false>
; __device__ __forceinline__ void gemm_phase(PG8_LAS unsigned char* lds, const Gemm g, const Sched& S, const Epi& E, const int tid) {
;     ...
;         for (int t = 0; t < nt; t += 2) {
;             const bool last = (t == nt - 2);
;             const char* a1 = cA + (size_t)(t + 1) * kstep;
;             const char* a2 = last ? nA : cA + (size_t)(t + 2) * kstep; const char* b2 = last ? nB : cB + (size_t)(t + 2) * kstep;
;             const char* a3 = a2 + kstep; const char* b3 = b2 + kstep;
;             if (last && has_next) S.a_ready(nxt);
;     ...
;             PG8_WAIT_V(8); PG8_WAIT_L(0); PG8_BAR; PG8_MMA(0, 0, At, B0); PG8_MMA(0, 1, At, B1); PG8_BAR; PG8_SCHED;
;             PG8_LDA(At, 1, 1); PG8_STAGE(PG8_SB(1, 0), b3, voffB); PG8_STAGE(PG8_SB(1, 1), b3 + hstepB, voffB); PG8_STAGE(PG8_SA(1, 0), a3, voffA);
;             PG8_WAIT_V(8); PG8_WAIT_L(0); PG8_BAR; PG8_MMA(1, 0, At, B0); PG8_MMA(1, 1, At, B1); PG8_BAR; PG8_SCHED;
	s_add_i32 s8, s61, s45
	v_lshl_add_u64 v[164:165], v[164:165], 0, s[38:39]
	s_mov_b32 m0, s8
	ds_read_b128 v[192:195], v198 offset:49152
	ds_read_b128 v[220:223], v198 offset:50176
	ds_read_b128 v[224:227], v198 offset:51200
	ds_read_b128 v[228:231], v198 offset:52224
	ds_read_b128 v[232:235], v198 offset:53248
	ds_read_b128 v[236:239], v198 offset:54272
	ds_read_b128 v[240:243], v198 offset:55296
	ds_read_b128 v[244:247], v198 offset:56320
	global_load_lds_dwordx4 v[164:165], off
	s_add_i32 m0, s8, 0x2000
	s_add_u32 s8, s34, 0x40080
	v_lshl_add_u64 v[164:165], v[166:167], 0, s[38:39]
	s_addc_u32 s9, s35, 0
	s_add_i32 s34, s62, s45
	global_load_lds_dwordx4 v[164:165], off
	v_lshl_add_u64 v[164:165], s[8:9], 0, v[184:185]
	s_mov_b32 m0, s34
	s_nop 0
	global_load_lds_dwordx4 v[164:165], off
	v_lshl_add_u64 v[164:165], s[8:9], 0, v[180:181]
	s_add_i32 m0, s34, 0x2000
	s_nop 0
	global_load_lds_dwordx4 v[164:165], off
	v_lshl_add_u64 v[164:165], v[196:197], 0, s[38:39]
	s_mov_b32 m0, s52
	s_nop 0
	global_load_lds_dwordx4 v[164:165], off
	v_lshl_add_u64 v[164:165], v[200:201], 0, s[38:39]
	s_mov_b32 m0, s53
	s_nop 0
	global_load_lds_dwordx4 v[164:165], off
	s_waitcnt vmcnt(8)
	s_waitcnt lgkmcnt(0)
	s_barrier
	s_setprio 1
	s_waitcnt lgkmcnt(0)
	v_mfma_f32_16x16x32_bf16 v[62:65], v[130:133], v[192:195], v[62:65]
	v_mfma_f32_16x16x32_bf16 v[58:61], v[138:141], v[192:195], v[58:61]
	v_mfma_f32_16x16x32_bf16 v[54:57], v[130:133], v[224:227], v[54:57]
	v_mfma_f32_16x16x32_bf16 v[50:53], v[138:141], v[224:227], v[50:53]
	v_mfma_f32_16x16x32_bf16 v[46:49], v[130:133], v[232:235], v[46:49]
	v_mfma_f32_16x16x32_bf16 v[42:45], v[138:141], v[232:235], v[42:45]
	v_mfma_f32_16x16x32_bf16 v[38:41], v[130:133], v[240:243], v[38:41]
	v_mfma_f32_16x16x32_bf16 v[34:37], v[138:141], v[240:243], v[34:37]
	v_mfma_f32_16x16x32_bf16 v[62:65], v[134:137], v[220:223], v[62:65]
	v_mfma_f32_16x16x32_bf16 v[58:61], v[142:145], v[220:223], v[58:61]
	v_mfma_f32_16x16x32_bf16 v[54:57], v[134:137], v[228:231], v[54:57]
	v_mfma_f32_16x16x32_bf16 v[50:53], v[142:145], v[228:231], v[50:53]
	v_mfma_f32_16x16x32_bf16 v[46:49], v[134:137], v[236:239], v[46:49]
	v_mfma_f32_16x16x32_bf16 v[42:45], v[142:145], v[236:239], v[42:45]
	v_mfma_f32_16x16x32_bf16 v[38:41], v[134:137], v[244:247], v[38:41]
	v_mfma_f32_16x16x32_bf16 v[34:37], v[142:145], v[244:247], v[34:37]
	s_setprio 0
	s_setprio 1
	v_mfma_f32_16x16x32_bf16 v[28:31], v[146:149], v[192:195], v[28:31]
	v_mfma_f32_16x16x32_bf16 v[24:27], v[154:157], v[192:195], v[24:27]
	v_mfma_f32_16x16x32_bf16 v[20:23], v[146:149], v[224:227], v[20:23]
	v_mfma_f32_16x16x32_bf16 v[16:19], v[154:157], v[224:227], v[16:19]
	v_mfma_f32_16x16x32_bf16 v[12:15], v[146:149], v[232:235], v[12:15]
	v_mfma_f32_16x16x32_bf16 v[8:11], v[154:157], v[232:235], v[8:11]
	v_mfma_f32_16x16x32_bf16 v[4:7], v[146:149], v[240:243], v[4:7]
	v_mfma_f32_16x16x32_bf16 v[0:3], v[154:157], v[240:243], v[0:3]
	v_mfma_f32_16x16x32_bf16 v[28:31], v[150:153], v[220:223], v[28:31]
	v_mfma_f32_16x16x32_bf16 v[24:27], v[158:161], v[220:223], v[24:27]
	v_mfma_f32_16x16x32_bf16 v[20:23], v[150:153], v[228:231], v[20:23]
	v_mfma_f32_16x16x32_bf16 v[16:19], v[158:161], v[228:231], v[16:19]
	v_mfma_f32_16x16x32_bf16 v[12:15], v[150:153], v[236:239], v[12:15]
	v_mfma_f32_16x16x32_bf16 v[8:11], v[158:161], v[236:239], v[8:11]
	v_mfma_f32_16x16x32_bf16 v[4:7], v[150:153], v[244:247], v[4:7]
	v_mfma_f32_16x16x32_bf16 v[0:3], v[158:161], v[244:247], v[0:3]
	s_setprio 0
	s_add_u32 s58, s58, 0x100
	s_addc_u32 s59, s59, 0
	s_mov_b64 s[8:9], s[6:7]
	s_mov_b32 s36, s60
	s_add_i32 s60, s36, 2
	s_add_u32 s6, s8, 0x100
	s_addc_u32 s7, s9, 0
	s_add_i32 s61, 0, 0x10000
	s_cmp_eq_u32 s57, s36
	s_cselect_b32 s37, s29, s7
	s_cselect_b32 s36, s28, s6
	s_cselect_b32 s35, s31, s59
	s_cselect_b32 s34, s30, s58
	s_add_i32 s62, 0, 0x14000
	v_add_u32_e32 v142, s61, v163
	v_add_u32_e32 v158, s62, v163
	s_add_i32 vcc_lo, s60, -2
	s_cmp_ge_u32 vcc_lo, s27
	s_barrier
	s_cbranch_scc0 .Lrot_457
	s_and_b64 vcc, exec, s[24:25]
	s_cbranch_vccz .LBB0_460
	s_barrier

; #define PG8_STAGE(bufoff, gbase, voff) do { _Pragma("unroll") for (int _i = 0; _i < 2; ++_i) \
;         __builtin_amdgcn_global_load_lds((const unsigned*)((const char*)(gbase) + (voff)[_i]), (PG8_LAS unsigned*)(lds + (bufoff) + ldsw + _i * 8192), 16, 0, 0); } while (0)
; #define PG8_WAIT_V(n) asm volatile("s_waitcnt vmcnt(" #n ")" ::: "memory")
; #define PG8_WAIT_L(n) asm volatile("s_waitcnt lgkmcnt(" #n ")" ::: "memory")
; #define PG8_BAR __builtin_amdgcn_s_barrier()
; #define PG8_SCHED __builtin_amdgcn_sched_barrier(0)
; template <class Epi, class Sched, bool ALIGN_EPI = false, bool SP2 = false, bool FP8 = false>
; __device__ __forceinline__ void gemm_phase(PG8_LAS unsigned char* lds, const Gemm g, const Sched& S, const Epi& E, const int tid) {
;     ...
;             PG8_LDB(B0, 0, 0); PG8_LDB(B1, 0, 1); PG8_SCHED; PG8_LDA(At, 0, 0); PG8_STAGE(PG8_SA(1, 1), a1 + hstepA, voffA);
;             PG8_WAIT_V(8); PG8_WAIT_L(0); PG8_BAR; PG8_MMA(0, 0, At, B0); PG8_MMA(0, 1, At, B1); PG8_BAR; PG8_SCHED;
.Lrot_589:
	ds_read_b128 v[130:133], v142
	ds_read_b128 v[134:137], v142 offset:1024
	ds_read_b128 v[138:141], v142 offset:2048
	ds_read_b128 v[142:145], v142 offset:3072
	ds_read_b128 v[146:149], v158
	ds_read_b128 v[150:153], v158 offset:1024
	ds_read_b128 v[154:157], v158 offset:2048
	ds_read_b128 v[158:161], v158 offset:3072
	v_lshl_add_u64 v[164:165], s[8:9], 0, v[188:189]
	s_add_i32 m0, s53, 0xc000
	ds_read_b128 v[192:195], v220
	ds_read_b128 v[196:199], v220 offset:1024
	ds_read_b128 v[222:225], v220 offset:2048
	ds_read_b128 v[226:229], v220 offset:3072
	ds_read_b128 v[230:233], v220 offset:4096
	ds_read_b128 v[234:237], v220 offset:5120
	ds_read_b128 v[238:241], v220 offset:6144
	ds_read_b128 v[242:245], v220 offset:7168
	global_load_lds_dwordx4 v[164:165], off
	v_lshl_add_u64 v[164:165], s[8:9], 0, v[190:191]
	s_add_i32 m0, s53, 0xe000
	s_nop 0
	global_load_lds_dwordx4 v[164:165], off
	s_cmp_eq_i32 s62, -2
	s_cbranch_scc1 .Lskw_3_0
	s_waitcnt vmcnt(8)

; #define PG8_STAGE(bufoff, gbase, voff) do { _Pragma("unroll") for (int _i = 0; _i < 2; ++_i) \
;         __builtin_amdgcn_global_load_lds((const unsigned*)((const char*)(gbase) + (voff)[_i]), (PG8_LAS unsigned*)(lds + (bufoff) + ldsw + _i * 8192), 16, 0, 0); } while (0)
; #define PG8_WAIT_V(n) asm volatile("s_waitcnt vmcnt(" #n ")" ::: "memory")
; #define PG8_WAIT_L(n) asm volatile("s_waitcnt lgkmcnt(" #n ")" ::: "memory")
; #define PG8_BAR __builtin_amdgcn_s_barrier()
; #define PG8_SCHED __builtin_amdgcn_sched_barrier(0)
; template <class Epi, class Sched, bool ALIGN_EPI = false, bool SP2 = false, bool FP8 = false>
; __device__ __forceinline__ void gemm_phase(PG8_LAS unsigned char* lds, const Gemm g, const Sched& S, const Epi& E, const int tid) {
;     ...
;             PG8_WAIT_V(8); PG8_WAIT_L(0); PG8_BAR; PG8_MMA(0, 0, At, B0); PG8_MMA(0, 1, At, B1); PG8_BAR; PG8_SCHED;
;             PG8_LDA(At, 0, 1); PG8_STAGE(PG8_SB(0, 0), b2, voffB); PG8_STAGE(PG8_SB(0, 1), b2 + hstepB, voffB); PG8_STAGE(PG8_SA(0, 0), a2, voffA);
;             PG8_WAIT_V(8); PG8_WAIT_L(0); PG8_BAR; PG8_MMA(1, 0, At, B0); PG8_MMA(1, 1, At, B1); PG8_BAR; PG8_SCHED;
;             PG8_LDB(B0, 1, 0); PG8_LDB(B1, 1, 1); PG8_SCHED; PG8_LDA(At, 1, 0); PG8_STAGE(PG8_SA(0, 1), a2 + hstepA, voffA);
;             PG8_WAIT_V(8); PG8_WAIT_L(0); PG8_BAR; PG8_MMA(0, 0, At, B0); PG8_MMA(0, 1, At, B1); PG8_BAR; PG8_SCHED;
.Lskw_3_1:
	s_waitcnt lgkmcnt(0)
	s_barrier
	s_setprio 1
	s_waitcnt lgkmcnt(0)
	v_mfma_f32_16x16x32_bf16 v[62:65], v[130:133], v[192:195], v[62:65]
	v_mfma_f32_16x16x32_bf16 v[58:61], v[138:141], v[192:195], v[58:61]
	v_mfma_f32_16x16x32_bf16 v[46:49], v[130:133], v[222:225], v[46:49]
	v_mfma_f32_16x16x32_bf16 v[42:45], v[138:141], v[222:225], v[42:45]
	v_mfma_f32_16x16x32_bf16 v[28:31], v[130:133], v[230:233], v[28:31]
	v_mfma_f32_16x16x32_bf16 v[24:27], v[138:141], v[230:233], v[24:27]
	v_mfma_f32_16x16x32_bf16 v[12:15], v[130:133], v[238:241], v[12:15]
	v_mfma_f32_16x16x32_bf16 v[8:11], v[138:141], v[238:241], v[8:11]
	v_mfma_f32_16x16x32_bf16 v[62:65], v[134:137], v[196:199], v[62:65]
	v_mfma_f32_16x16x32_bf16 v[58:61], v[142:145], v[196:199], v[58:61]
	v_mfma_f32_16x16x32_bf16 v[46:49], v[134:137], v[226:229], v[46:49]
	v_mfma_f32_16x16x32_bf16 v[42:45], v[142:145], v[226:229], v[42:45]
	v_mfma_f32_16x16x32_bf16 v[28:31], v[134:137], v[234:237], v[28:31]
	v_mfma_f32_16x16x32_bf16 v[24:27], v[142:145], v[234:237], v[24:27]
	v_mfma_f32_16x16x32_bf16 v[12:15], v[134:137], v[242:245], v[12:15]
	v_mfma_f32_16x16x32_bf16 v[8:11], v[142:145], v[242:245], v[8:11]
	s_setprio 0
	s_setprio 1
	v_mfma_f32_16x16x32_bf16 v[54:57], v[146:149], v[192:195], v[54:57]
	v_mfma_f32_16x16x32_bf16 v[50:53], v[154:157], v[192:195], v[50:53]
	v_mfma_f32_16x16x32_bf16 v[38:41], v[146:149], v[222:225], v[38:41]
	v_mfma_f32_16x16x32_bf16 v[34:37], v[154:157], v[222:225], v[34:37]
	v_mfma_f32_16x16x32_bf16 v[20:23], v[146:149], v[230:233], v[20:23]
	v_mfma_f32_16x16x32_bf16 v[16:19], v[154:157], v[230:233], v[16:19]
	v_mfma_f32_16x16x32_bf16 v[4:7], v[146:149], v[238:241], v[4:7]
	v_mfma_f32_16x16x32_bf16 v[0:3], v[154:157], v[238:241], v[0:3]
	v_mfma_f32_16x16x32_bf16 v[54:57], v[150:153], v[196:199], v[54:57]
	v_mfma_f32_16x16x32_bf16 v[50:53], v[158:161], v[196:199], v[50:53]
	v_mfma_f32_16x16x32_bf16 v[38:41], v[150:153], v[226:229], v[38:41]
	v_mfma_f32_16x16x32_bf16 v[34:37], v[158:161], v[226:229], v[34:37]
	v_mfma_f32_16x16x32_bf16 v[20:23], v[150:153], v[234:237], v[20:23]
	v_mfma_f32_16x16x32_bf16 v[16:19], v[158:161], v[234:237], v[16:19]
	v_mfma_f32_16x16x32_bf16 v[4:7], v[150:153], v[242:245], v[4:7]
	v_mfma_f32_16x16x32_bf16 v[0:3], v[158:161], v[242:245], v[0:3]
	s_setprio 0
	s_barrier
	s_add_i32 s63, 0, 0x18000
	s_add_i32 s64, 0, 0x1c000
	v_add_u32_e32 v142, s63, v163
	v_add_u32_e32 v158, s64, v163
	ds_read_b128 v[130:133], v142
	ds_read_b128 v[134:137], v142 offset:1024
	ds_read_b128 v[138:141], v142 offset:2048
	ds_read_b128 v[142:145], v142 offset:3072
	ds_read_b128 v[146:149], v158
	ds_read_b128 v[150:153], v158 offset:1024
	ds_read_b128 v[154:157], v158 offset:2048
	ds_read_b128 v[158:161], v158 offset:3072
	s_add_u32 s46, s46, 0x80000
	s_addc_u32 s47, s47, 0
	s_mov_b32 m0, s55
	v_lshl_add_u64 v[248:249], s[46:47], 0, v[186:187]
	ds_read_b128 v[192:195], v220 offset:32768
	ds_read_b128 v[196:199], v220 offset:33792
	ds_read_b128 v[222:225], v220 offset:34816
	ds_read_b128 v[226:229], v220 offset:35840
	ds_read_b128 v[230:233], v220 offset:36864
	ds_read_b128 v[234:237], v220 offset:37888
	ds_read_b128 v[238:241], v220 offset:38912
	ds_read_b128 v[242:245], v220 offset:39936
	global_load_lds_dwordx4 v[248:249], off
	v_lshl_add_u64 v[248:249], s[46:47], 0, v[182:183]
	s_mov_b32 m0, s56
	s_nop 0
	global_load_lds_dwordx4 v[248:249], off
	s_waitcnt vmcnt(8)
	s_waitcnt lgkmcnt(0)
	s_barrier
	s_setprio 1
	s_waitcnt lgkmcnt(0)
	v_mfma_f32_16x16x32_bf16 v[126:129], v[130:133], v[192:195], v[126:129]
	v_mfma_f32_16x16x32_bf16 v[122:125], v[138:141], v[192:195], v[122:125]
	v_mfma_f32_16x16x32_bf16 v[110:113], v[130:133], v[222:225], v[110:113]
	v_mfma_f32_16x16x32_bf16 v[106:109], v[138:141], v[222:225], v[106:109]
	v_mfma_f32_16x16x32_bf16 v[94:97], v[130:133], v[230:233], v[94:97]
	v_mfma_f32_16x16x32_bf16 v[90:93], v[138:141], v[230:233], v[90:93]
	v_mfma_f32_16x16x32_bf16 v[78:81], v[130:133], v[238:241], v[78:81]
	v_mfma_f32_16x16x32_bf16 v[74:77], v[138:141], v[238:241], v[74:77]
	v_mfma_f32_16x16x32_bf16 v[126:129], v[134:137], v[196:199], v[126:129]
	v_mfma_f32_16x16x32_bf16 v[122:125], v[142:145], v[196:199], v[122:125]
	v_mfma_f32_16x16x32_bf16 v[110:113], v[134:137], v[226:229], v[110:113]
	v_mfma_f32_16x16x32_bf16 v[106:109], v[142:145], v[226:229], v[106:109]
	v_mfma_f32_16x16x32_bf16 v[94:97], v[134:137], v[234:237], v[94:97]
	v_mfma_f32_16x16x32_bf16 v[90:93], v[142:145], v[234:237], v[90:93]
	v_mfma_f32_16x16x32_bf16 v[78:81], v[134:137], v[242:245], v[78:81]
	v_mfma_f32_16x16x32_bf16 v[74:77], v[142:145], v[242:245], v[74:77]
	s_setprio 0
	s_setprio 1
	v_mfma_f32_16x16x32_bf16 v[118:121], v[146:149], v[192:195], v[118:121]
	v_mfma_f32_16x16x32_bf16 v[114:117], v[154:157], v[192:195], v[114:117]
	v_mfma_f32_16x16x32_bf16 v[102:105], v[146:149], v[222:225], v[102:105]
	v_mfma_f32_16x16x32_bf16 v[98:101], v[154:157], v[222:225], v[98:101]
	v_mfma_f32_16x16x32_bf16 v[86:89], v[146:149], v[230:233], v[86:89]
	v_mfma_f32_16x16x32_bf16 v[82:85], v[154:157], v[230:233], v[82:85]
	v_mfma_f32_16x16x32_bf16 v[70:73], v[146:149], v[238:241], v[70:73]
	v_mfma_f32_16x16x32_bf16 v[66:69], v[154:157], v[238:241], v[66:69]
	v_mfma_f32_16x16x32_bf16 v[118:121], v[150:153], v[196:199], v[118:121]
	v_mfma_f32_16x16x32_bf16 v[114:117], v[158:161], v[196:199], v[114:117]
	v_mfma_f32_16x16x32_bf16 v[102:105], v[150:153], v[226:229], v[102:105]
	v_mfma_f32_16x16x32_bf16 v[98:101], v[158:161], v[226:229], v[98:101]
	v_mfma_f32_16x16x32_bf16 v[86:89], v[150:153], v[234:237], v[86:89]
	v_mfma_f32_16x16x32_bf16 v[82:85], v[158:161], v[234:237], v[82:85]
	v_mfma_f32_16x16x32_bf16 v[70:73], v[150:153], v[242:245], v[70:73]
	v_mfma_f32_16x16x32_bf16 v[66:69], v[158:161], v[242:245], v[66:69]
	s_setprio 0
	s_barrier
; #define PG8_STAGE(bufoff, gbase, voff) do { _Pragma("unroll") for (int _i = 0; _i < 2; ++_i) \
;         __builtin_amdgcn_global_load_lds((const unsigned*)((const char*)(gbase) + (voff)[_i]), (PG8_LAS unsigned*)(lds + (bufoff) + ldsw + _i * 8192), 16, 0, 0); } while (0)
; #define PG8_WAIT_V(n) asm volatile("s_waitcnt vmcnt(" #n ")" ::: "memory")
; #define PG8_WAIT_L(n) asm volatile("s_waitcnt lgkmcnt(" #n ")" ::: "memory")
; #define PG8_BAR __builtin_amdgcn_s_barrier()
; #define PG8_SCHED __builtin_amdgcn_sched_barrier(0)
; template <class Epi, class Sched, bool ALIGN_EPI = false, bool SP2 = false, bool FP8 = false>
; __device__ __forceinline__ void gemm_phase(PG8_LAS unsigned char* lds, const Gemm g, const Sched& S, const Epi& E, const int tid) {
;     ...
;         for (int t = 0; t < nt; t += 2) {
;             const bool last = (t == nt - 2);
;             const char* a1 = cA + (size_t)(t + 1) * kstep;
;             const char* a2 = last ? nA : cA + (size_t)(t + 2) * kstep; const char* b2 = last ? nB : cB + (size_t)(t + 2) * kstep;
;             const char* a3 = a2 + kstep; const char* b3 = b2 + kstep;
;             if (last && has_next) S.a_ready(nxt);
;     ...
;             PG8_WAIT_V(8); PG8_WAIT_L(0); PG8_BAR; PG8_MMA(0, 0, At, B0); PG8_MMA(0, 1, At, B1); PG8_BAR; PG8_SCHED;
;             PG8_LDA(At, 1, 1); PG8_STAGE(PG8_SB(1, 0), b3, voffB); PG8_STAGE(PG8_SB(1, 1), b3 + hstepB, voffB); PG8_STAGE(PG8_SA(1, 0), a3, voffA);
;             PG8_WAIT_V(8); PG8_WAIT_L(0); PG8_BAR; PG8_MMA(1, 0, At, B0); PG8_MMA(1, 1, At, B1); PG8_BAR; PG8_SCHED;
	s_add_i32 s46, s63, s52
	v_lshl_add_u64 v[164:165], v[164:165], 0, s[38:39]
	s_mov_b32 m0, s46
	ds_read_b128 v[192:195], v220 offset:49152
	ds_read_b128 v[196:199], v220 offset:50176
	ds_read_b128 v[222:225], v220 offset:51200
	ds_read_b128 v[226:229], v220 offset:52224
	ds_read_b128 v[230:233], v220 offset:53248
	ds_read_b128 v[234:237], v220 offset:54272
	ds_read_b128 v[238:241], v220 offset:55296
	ds_read_b128 v[242:245], v220 offset:56320
	global_load_lds_dwordx4 v[164:165], off
	s_add_i32 m0, s46, 0x2000
	s_add_u32 s44, s44, 0x80080
	v_lshl_add_u64 v[164:165], v[166:167], 0, s[38:39]
	s_addc_u32 s45, s45, 0
	s_add_i32 s46, s64, s52
	global_load_lds_dwordx4 v[164:165], off
	v_lshl_add_u64 v[164:165], s[44:45], 0, v[184:185]
	s_mov_b32 m0, s46
	s_nop 0
	global_load_lds_dwordx4 v[164:165], off
	v_lshl_add_u64 v[164:165], s[44:45], 0, v[180:181]
	s_add_i32 m0, s46, 0x2000
	s_nop 0
	global_load_lds_dwordx4 v[164:165], off
	v_lshl_add_u64 v[164:165], v[200:201], 0, s[38:39]
	s_mov_b32 m0, s0
	s_nop 0
	global_load_lds_dwordx4 v[164:165], off
	v_lshl_add_u64 v[164:165], v[246:247], 0, s[38:39]
	s_mov_b32 m0, s57
	s_nop 0
	global_load_lds_dwordx4 v[164:165], off
	s_waitcnt vmcnt(8)
	s_waitcnt lgkmcnt(0)
	s_barrier
	s_setprio 1
	s_waitcnt lgkmcnt(0)
	v_mfma_f32_16x16x32_bf16 v[62:65], v[130:133], v[192:195], v[62:65]
	v_mfma_f32_16x16x32_bf16 v[58:61], v[138:141], v[192:195], v[58:61]
	v_mfma_f32_16x16x32_bf16 v[46:49], v[130:133], v[222:225], v[46:49]
	v_mfma_f32_16x16x32_bf16 v[42:45], v[138:141], v[222:225], v[42:45]
	v_mfma_f32_16x16x32_bf16 v[28:31], v[130:133], v[230:233], v[28:31]
	v_mfma_f32_16x16x32_bf16 v[24:27], v[138:141], v[230:233], v[24:27]
	v_mfma_f32_16x16x32_bf16 v[12:15], v[130:133], v[238:241], v[12:15]
	v_mfma_f32_16x16x32_bf16 v[8:11], v[138:141], v[238:241], v[8:11]
	v_mfma_f32_16x16x32_bf16 v[62:65], v[134:137], v[196:199], v[62:65]
	v_mfma_f32_16x16x32_bf16 v[58:61], v[142:145], v[196:199], v[58:61]
	v_mfma_f32_16x16x32_bf16 v[46:49], v[134:137], v[226:229], v[46:49]
	v_mfma_f32_16x16x32_bf16 v[42:45], v[142:145], v[226:229], v[42:45]
	v_mfma_f32_16x16x32_bf16 v[28:31], v[134:137], v[234:237], v[28:31]
	v_mfma_f32_16x16x32_bf16 v[24:27], v[142:145], v[234:237], v[24:27]
	v_mfma_f32_16x16x32_bf16 v[12:15], v[134:137], v[242:245], v[12:15]
	v_mfma_f32_16x16x32_bf16 v[8:11], v[142:145], v[242:245], v[8:11]
	s_setprio 0
	s_setprio 1
	v_mfma_f32_16x16x32_bf16 v[54:57], v[146:149], v[192:195], v[54:57]
	v_mfma_f32_16x16x32_bf16 v[50:53], v[154:157], v[192:195], v[50:53]
	v_mfma_f32_16x16x32_bf16 v[38:41], v[146:149], v[222:225], v[38:41]
	v_mfma_f32_16x16x32_bf16 v[34:37], v[154:157], v[222:225], v[34:37]
	v_mfma_f32_16x16x32_bf16 v[20:23], v[146:149], v[230:233], v[20:23]
	v_mfma_f32_16x16x32_bf16 v[16:19], v[154:157], v[230:233], v[16:19]
	v_mfma_f32_16x16x32_bf16 v[4:7], v[146:149], v[238:241], v[4:7]
	v_mfma_f32_16x16x32_bf16 v[0:3], v[154:157], v[238:241], v[0:3]
	v_mfma_f32_16x16x32_bf16 v[54:57], v[150:153], v[196:199], v[54:57]
	v_mfma_f32_16x16x32_bf16 v[50:53], v[158:161], v[196:199], v[50:53]
	v_mfma_f32_16x16x32_bf16 v[38:41], v[150:153], v[226:229], v[38:41]
	v_mfma_f32_16x16x32_bf16 v[34:37], v[158:161], v[226:229], v[34:37]
	v_mfma_f32_16x16x32_bf16 v[20:23], v[150:153], v[234:237], v[20:23]
	v_mfma_f32_16x16x32_bf16 v[16:19], v[158:161], v[234:237], v[16:19]
	v_mfma_f32_16x16x32_bf16 v[4:7], v[150:153], v[242:245], v[4:7]
	v_mfma_f32_16x16x32_bf16 v[0:3], v[158:161], v[242:245], v[0:3]
	s_setprio 0
	s_add_i32 s62, s62, 2
	s_add_u32 s8, s8, 0x100
	s_addc_u32 s9, s9, 0
	s_add_u32 s60, s60, 0x100
	s_addc_u32 s61, s61, 0
	s_add_u32 s44, s8, 0xfff80080
	s_addc_u32 s45, s9, -1
	s_add_i32 s63, 0, 0x10000
	s_cmp_eq_u32 s62, 28
	s_cselect_b32 s47, s33, s45
	s_cselect_b32 s46, s35, s44
	s_cselect_b32 s45, s31, s61
	s_cselect_b32 s44, s59, s60
	s_add_i32 s66, 0, 0x14000
	v_add_u32_e32 v142, s63, v163
	v_add_u32_e32 v158, s66, v163
	s_cmp_gt_u32 s62, 29
	s_barrier
	s_cbranch_scc0 .Lrot_589
	s_and_b64 vcc, exec, s[26:27]
	s_cbranch_vccz .LBB0_592
	s_barrier

; #define PG8_STAGE(bufoff, gbase, voff) do { _Pragma("unroll") for (int _i = 0; _i < 2; ++_i) \
;         __builtin_amdgcn_global_load_lds((const unsigned*)((const char*)(gbase) + (voff)[_i]), (PG8_LAS unsigned*)(lds + (bufoff) + ldsw + _i * 8192), 16, 0, 0); } while (0)
; #define PG8_WAIT_V(n) asm volatile("s_waitcnt vmcnt(" #n ")" ::: "memory")
; #define PG8_WAIT_L(n) asm volatile("s_waitcnt lgkmcnt(" #n ")" ::: "memory")
; #define PG8_BAR __builtin_amdgcn_s_barrier()
; #define PG8_SCHED __builtin_amdgcn_sched_barrier(0)
; template <class Epi, class Sched, bool ALIGN_EPI = false, bool SP2 = false, bool FP8 = false>
; __device__ __forceinline__ void gemm_phase(PG8_LAS unsigned char* lds, const Gemm g, const Sched& S, const Epi& E, const int tid) {
;     ...
;             PG8_LDB(B0, 0, 0); PG8_LDB(B1, 0, 1); PG8_SCHED; PG8_LDA(At, 0, 0); PG8_STAGE(PG8_SA(1, 1), a1 + hstepA, voffA);
;             PG8_WAIT_V(8); PG8_WAIT_L(0); PG8_BAR; PG8_MMA(0, 0, At, B0); PG8_MMA(0, 1, At, B1); PG8_BAR; PG8_SCHED;
.Lrot_735:
	ds_read_b128 v[142:145], v153
	ds_read_b128 v[146:149], v153 offset:1024
	ds_read_b128 v[154:157], v153 offset:2048
	ds_read_b128 v[158:161], v153 offset:3072
	v_add_u32_e32 v153, s60, v150
	ds_read_b128 v[180:183], v153
	ds_read_b128 v[184:187], v153 offset:1024
	ds_read_b128 v[188:191], v153 offset:2048
	ds_read_b128 v[192:195], v153 offset:3072
	v_lshl_add_u64 v[164:165], s[30:31], 0, v[138:139]
	s_add_i32 m0, s47, 0xc000
	ds_read_b128 v[196:199], v152
	ds_read_b128 v[220:223], v152 offset:1024
	ds_read_b128 v[224:227], v152 offset:2048
	ds_read_b128 v[228:231], v152 offset:3072
	ds_read_b128 v[232:235], v152 offset:4096
	ds_read_b128 v[236:239], v152 offset:5120
	ds_read_b128 v[240:243], v152 offset:6144
	ds_read_b128 v[244:247], v152 offset:7168
	global_load_lds_dwordx4 v[164:165], off
	v_lshl_add_u64 v[164:165], s[30:31], 0, v[140:141]
	s_add_i32 m0, s47, 0xe000
	s_nop 0
	global_load_lds_dwordx4 v[164:165], off
	s_cmp_eq_i32 s56, -2
	s_cbranch_scc1 .Lskw_4_0
	s_waitcnt vmcnt(8)

; #define PG8_STAGE(bufoff, gbase, voff) do { _Pragma("unroll") for (int _i = 0; _i < 2; ++_i) \
;         __builtin_amdgcn_global_load_lds((const unsigned*)((const char*)(gbase) + (voff)[_i]), (PG8_LAS unsigned*)(lds + (bufoff) + ldsw + _i * 8192), 16, 0, 0); } while (0)
; #define PG8_WAIT_V(n) asm volatile("s_waitcnt vmcnt(" #n ")" ::: "memory")
; #define PG8_WAIT_L(n) asm volatile("s_waitcnt lgkmcnt(" #n ")" ::: "memory")
; #define PG8_BAR __builtin_amdgcn_s_barrier()
; #define PG8_SCHED __builtin_amdgcn_sched_barrier(0)
; template <class Epi, class Sched, bool ALIGN_EPI = false, bool SP2 = false, bool FP8 = false>
; __device__ __forceinline__ void gemm_phase(PG8_LAS unsigned char* lds, const Gemm g, const Sched& S, const Epi& E, const int tid) {
;     ...
;             PG8_WAIT_V(8); PG8_WAIT_L(0); PG8_BAR; PG8_MMA(0, 0, At, B0); PG8_MMA(0, 1, At, B1); PG8_BAR; PG8_SCHED;
;             PG8_LDA(At, 0, 1); PG8_STAGE(PG8_SB(0, 0), b2, voffB); PG8_STAGE(PG8_SB(0, 1), b2 + hstepB, voffB); PG8_STAGE(PG8_SA(0, 0), a2, voffA);
;             PG8_WAIT_V(8); PG8_WAIT_L(0); PG8_BAR; PG8_MMA(1, 0, At, B0); PG8_MMA(1, 1, At, B1); PG8_BAR; PG8_SCHED;
;             PG8_LDB(B0, 1, 0); PG8_LDB(B1, 1, 1); PG8_SCHED; PG8_LDA(At, 1, 0); PG8_STAGE(PG8_SA(0, 1), a2 + hstepA, voffA);
;             PG8_WAIT_V(8); PG8_WAIT_L(0); PG8_BAR; PG8_MMA(0, 0, At, B0); PG8_MMA(0, 1, At, B1); PG8_BAR; PG8_SCHED;
.Lskw_4_1:
	s_waitcnt lgkmcnt(0)
	s_barrier
	s_setprio 1
	s_waitcnt lgkmcnt(0)
	v_mfma_f32_16x16x32_bf16 v[62:65], v[142:145], v[196:199], v[62:65]
	v_mfma_f32_16x16x32_bf16 v[58:61], v[154:157], v[196:199], v[58:61]
	v_mfma_f32_16x16x32_bf16 v[46:49], v[142:145], v[224:227], v[46:49]
	v_mfma_f32_16x16x32_bf16 v[42:45], v[154:157], v[224:227], v[42:45]
	v_mfma_f32_16x16x32_bf16 v[28:31], v[142:145], v[232:235], v[28:31]
	v_mfma_f32_16x16x32_bf16 v[24:27], v[154:157], v[232:235], v[24:27]
	v_mfma_f32_16x16x32_bf16 v[12:15], v[142:145], v[240:243], v[12:15]
	v_mfma_f32_16x16x32_bf16 v[8:11], v[154:157], v[240:243], v[8:11]
	v_mfma_f32_16x16x32_bf16 v[62:65], v[146:149], v[220:223], v[62:65]
	v_mfma_f32_16x16x32_bf16 v[58:61], v[158:161], v[220:223], v[58:61]
	v_mfma_f32_16x16x32_bf16 v[46:49], v[146:149], v[228:231], v[46:49]
	v_mfma_f32_16x16x32_bf16 v[42:45], v[158:161], v[228:231], v[42:45]
	v_mfma_f32_16x16x32_bf16 v[28:31], v[146:149], v[236:239], v[28:31]
	v_mfma_f32_16x16x32_bf16 v[24:27], v[158:161], v[236:239], v[24:27]
	v_mfma_f32_16x16x32_bf16 v[12:15], v[146:149], v[244:247], v[12:15]
	v_mfma_f32_16x16x32_bf16 v[8:11], v[158:161], v[244:247], v[8:11]
	s_setprio 0
	s_setprio 1
	v_mfma_f32_16x16x32_bf16 v[54:57], v[180:183], v[196:199], v[54:57]
	v_mfma_f32_16x16x32_bf16 v[50:53], v[188:191], v[196:199], v[50:53]
	v_mfma_f32_16x16x32_bf16 v[38:41], v[180:183], v[224:227], v[38:41]
	v_mfma_f32_16x16x32_bf16 v[34:37], v[188:191], v[224:227], v[34:37]
	v_mfma_f32_16x16x32_bf16 v[20:23], v[180:183], v[232:235], v[20:23]
	v_mfma_f32_16x16x32_bf16 v[16:19], v[188:191], v[232:235], v[16:19]
	v_mfma_f32_16x16x32_bf16 v[4:7], v[180:183], v[240:243], v[4:7]
	v_mfma_f32_16x16x32_bf16 v[0:3], v[188:191], v[240:243], v[0:3]
	v_mfma_f32_16x16x32_bf16 v[54:57], v[184:187], v[220:223], v[54:57]
	v_mfma_f32_16x16x32_bf16 v[50:53], v[192:195], v[220:223], v[50:53]
	v_mfma_f32_16x16x32_bf16 v[38:41], v[184:187], v[228:231], v[38:41]
	v_mfma_f32_16x16x32_bf16 v[34:37], v[192:195], v[228:231], v[34:37]
	v_mfma_f32_16x16x32_bf16 v[20:23], v[184:187], v[236:239], v[20:23]
	v_mfma_f32_16x16x32_bf16 v[16:19], v[192:195], v[236:239], v[16:19]
	v_mfma_f32_16x16x32_bf16 v[4:7], v[184:187], v[244:247], v[4:7]
	v_mfma_f32_16x16x32_bf16 v[0:3], v[192:195], v[244:247], v[0:3]
	s_setprio 0
	s_barrier
	s_add_i32 s57, 0, 0x18000
	v_add_u32_e32 v153, s57, v150
	s_add_i32 s58, 0, 0x1c000
	ds_read_b128 v[142:145], v153
	ds_read_b128 v[146:149], v153 offset:1024
	ds_read_b128 v[154:157], v153 offset:2048
	ds_read_b128 v[158:161], v153 offset:3072
	v_add_u32_e32 v153, s58, v150
	ds_read_b128 v[180:183], v153
	ds_read_b128 v[184:187], v153 offset:1024
	ds_read_b128 v[188:191], v153 offset:2048
	ds_read_b128 v[192:195], v153 offset:3072
	s_add_u32 s36, s36, 0x80000
	s_addc_u32 s37, s37, 0
	s_mov_b32 m0, s49
	v_lshl_add_u64 v[250:251], s[36:37], 0, v[136:137]
	ds_read_b128 v[196:199], v152 offset:32768
	ds_read_b128 v[220:223], v152 offset:33792
	ds_read_b128 v[224:227], v152 offset:34816
	ds_read_b128 v[228:231], v152 offset:35840
	ds_read_b128 v[232:235], v152 offset:36864
	ds_read_b128 v[236:239], v152 offset:37888
	ds_read_b128 v[240:243], v152 offset:38912
	ds_read_b128 v[244:247], v152 offset:39936
	global_load_lds_dwordx4 v[250:251], off
	v_lshl_add_u64 v[250:251], s[36:37], 0, v[132:133]
	s_mov_b32 m0, s50
	s_nop 0
	global_load_lds_dwordx4 v[250:251], off
	s_waitcnt vmcnt(8)
	s_waitcnt lgkmcnt(0)
	s_barrier
	s_setprio 1
	s_waitcnt lgkmcnt(0)
	v_mfma_f32_16x16x32_bf16 v[126:129], v[142:145], v[196:199], v[126:129]
	v_mfma_f32_16x16x32_bf16 v[122:125], v[154:157], v[196:199], v[122:125]
	v_mfma_f32_16x16x32_bf16 v[110:113], v[142:145], v[224:227], v[110:113]
	v_mfma_f32_16x16x32_bf16 v[106:109], v[154:157], v[224:227], v[106:109]
	v_mfma_f32_16x16x32_bf16 v[94:97], v[142:145], v[232:235], v[94:97]
	v_mfma_f32_16x16x32_bf16 v[90:93], v[154:157], v[232:235], v[90:93]
	v_mfma_f32_16x16x32_bf16 v[78:81], v[142:145], v[240:243], v[78:81]
	v_mfma_f32_16x16x32_bf16 v[74:77], v[154:157], v[240:243], v[74:77]
	v_mfma_f32_16x16x32_bf16 v[126:129], v[146:149], v[220:223], v[126:129]
	v_mfma_f32_16x16x32_bf16 v[122:125], v[158:161], v[220:223], v[122:125]
	v_mfma_f32_16x16x32_bf16 v[110:113], v[146:149], v[228:231], v[110:113]
	v_mfma_f32_16x16x32_bf16 v[106:109], v[158:161], v[228:231], v[106:109]
	v_mfma_f32_16x16x32_bf16 v[94:97], v[146:149], v[236:239], v[94:97]
	v_mfma_f32_16x16x32_bf16 v[90:93], v[158:161], v[236:239], v[90:93]
	v_mfma_f32_16x16x32_bf16 v[78:81], v[146:149], v[244:247], v[78:81]
	v_mfma_f32_16x16x32_bf16 v[74:77], v[158:161], v[244:247], v[74:77]
	s_setprio 0
	s_setprio 1
	v_mfma_f32_16x16x32_bf16 v[118:121], v[180:183], v[196:199], v[118:121]
	v_mfma_f32_16x16x32_bf16 v[114:117], v[188:191], v[196:199], v[114:117]
	v_mfma_f32_16x16x32_bf16 v[102:105], v[180:183], v[224:227], v[102:105]
	v_mfma_f32_16x16x32_bf16 v[98:101], v[188:191], v[224:227], v[98:101]
	v_mfma_f32_16x16x32_bf16 v[86:89], v[180:183], v[232:235], v[86:89]
	v_mfma_f32_16x16x32_bf16 v[82:85], v[188:191], v[232:235], v[82:85]
	v_mfma_f32_16x16x32_bf16 v[70:73], v[180:183], v[240:243], v[70:73]
	v_mfma_f32_16x16x32_bf16 v[66:69], v[188:191], v[240:243], v[66:69]
	v_mfma_f32_16x16x32_bf16 v[118:121], v[184:187], v[220:223], v[118:121]
	v_mfma_f32_16x16x32_bf16 v[114:117], v[192:195], v[220:223], v[114:117]
	v_mfma_f32_16x16x32_bf16 v[102:105], v[184:187], v[228:231], v[102:105]
	v_mfma_f32_16x16x32_bf16 v[98:101], v[192:195], v[228:231], v[98:101]
	v_mfma_f32_16x16x32_bf16 v[86:89], v[184:187], v[236:239], v[86:89]
	v_mfma_f32_16x16x32_bf16 v[82:85], v[192:195], v[236:239], v[82:85]
	v_mfma_f32_16x16x32_bf16 v[70:73], v[184:187], v[244:247], v[70:73]
	v_mfma_f32_16x16x32_bf16 v[66:69], v[192:195], v[244:247], v[66:69]
	s_setprio 0
	s_barrier
; #define PG8_STAGE(bufoff, gbase, voff) do { _Pragma("unroll") for (int _i = 0; _i < 2; ++_i) \
;         __builtin_amdgcn_global_load_lds((const unsigned*)((const char*)(gbase) + (voff)[_i]), (PG8_LAS unsigned*)(lds + (bufoff) + ldsw + _i * 8192), 16, 0, 0); } while (0)
; #define PG8_WAIT_V(n) asm volatile("s_waitcnt vmcnt(" #n ")" ::: "memory")
; #define PG8_WAIT_L(n) asm volatile("s_waitcnt lgkmcnt(" #n ")" ::: "memory")
; #define PG8_BAR __builtin_amdgcn_s_barrier()
; #define PG8_SCHED __builtin_amdgcn_sched_barrier(0)
; template <class Epi, class Sched, bool ALIGN_EPI = false, bool SP2 = false, bool FP8 = false>
; __device__ __forceinline__ void gemm_phase(PG8_LAS unsigned char* lds, const Gemm g, const Sched& S, const Epi& E, const int tid) {
;     ...
;         for (int t = 0; t < nt; t += 2) {
;             const bool last = (t == nt - 2);
;             const char* a1 = cA + (size_t)(t + 1) * kstep;
;             const char* a2 = last ? nA : cA + (size_t)(t + 2) * kstep; const char* b2 = last ? nB : cB + (size_t)(t + 2) * kstep;
;             const char* a3 = a2 + kstep; const char* b3 = b2 + kstep;
;             if (last && has_next) S.a_ready(nxt);
;     ...
;             PG8_WAIT_V(8); PG8_WAIT_L(0); PG8_BAR; PG8_MMA(0, 0, At, B0); PG8_MMA(0, 1, At, B1); PG8_BAR; PG8_SCHED;
;             PG8_LDA(At, 1, 1); PG8_STAGE(PG8_SB(1, 0), b3, voffB); PG8_STAGE(PG8_SB(1, 1), b3 + hstepB, voffB); PG8_STAGE(PG8_SA(1, 0), a3, voffA);
;             PG8_WAIT_V(8); PG8_WAIT_L(0); PG8_BAR; PG8_MMA(1, 0, At, B0); PG8_MMA(1, 1, At, B1); PG8_BAR; PG8_SCHED;
	s_add_i32 s36, s57, s46
	v_lshl_add_u64 v[164:165], v[164:165], 0, s[38:39]
	s_mov_b32 m0, s36
	ds_read_b128 v[196:199], v152 offset:49152
	ds_read_b128 v[220:223], v152 offset:50176
	ds_read_b128 v[224:227], v152 offset:51200
	ds_read_b128 v[228:231], v152 offset:52224
	ds_read_b128 v[232:235], v152 offset:53248
	ds_read_b128 v[236:239], v152 offset:54272
	ds_read_b128 v[240:243], v152 offset:55296
	ds_read_b128 v[244:247], v152 offset:56320
	global_load_lds_dwordx4 v[164:165], off
	s_add_i32 m0, s36, 0x2000
	s_add_u32 s34, s34, 0x80080
	v_lshl_add_u64 v[164:165], v[166:167], 0, s[38:39]
	s_addc_u32 s35, s35, 0
	s_add_i32 s36, s58, s46
	global_load_lds_dwordx4 v[164:165], off
	v_lshl_add_u64 v[164:165], s[34:35], 0, v[134:135]
	s_mov_b32 m0, s36
	s_nop 0
	global_load_lds_dwordx4 v[164:165], off
	v_lshl_add_u64 v[164:165], s[34:35], 0, v[130:131]
	s_add_i32 m0, s36, 0x2000
	s_nop 0
	global_load_lds_dwordx4 v[164:165], off
	v_lshl_add_u64 v[164:165], v[200:201], 0, s[38:39]
	s_mov_b32 m0, s0
	s_nop 0
	global_load_lds_dwordx4 v[164:165], off
	v_lshl_add_u64 v[164:165], v[248:249], 0, s[38:39]
	s_mov_b32 m0, s51
	s_nop 0
	global_load_lds_dwordx4 v[164:165], off
	s_waitcnt vmcnt(8)
	s_waitcnt lgkmcnt(0)
	s_barrier
	s_setprio 1
	s_waitcnt lgkmcnt(0)
	v_mfma_f32_16x16x32_bf16 v[62:65], v[142:145], v[196:199], v[62:65]
	v_mfma_f32_16x16x32_bf16 v[58:61], v[154:157], v[196:199], v[58:61]
	v_mfma_f32_16x16x32_bf16 v[46:49], v[142:145], v[224:227], v[46:49]
	v_mfma_f32_16x16x32_bf16 v[42:45], v[154:157], v[224:227], v[42:45]
	v_mfma_f32_16x16x32_bf16 v[28:31], v[142:145], v[232:235], v[28:31]
	v_mfma_f32_16x16x32_bf16 v[24:27], v[154:157], v[232:235], v[24:27]
	v_mfma_f32_16x16x32_bf16 v[12:15], v[142:145], v[240:243], v[12:15]
	v_mfma_f32_16x16x32_bf16 v[8:11], v[154:157], v[240:243], v[8:11]
	v_mfma_f32_16x16x32_bf16 v[62:65], v[146:149], v[220:223], v[62:65]
	v_mfma_f32_16x16x32_bf16 v[58:61], v[158:161], v[220:223], v[58:61]
	v_mfma_f32_16x16x32_bf16 v[46:49], v[146:149], v[228:231], v[46:49]
	v_mfma_f32_16x16x32_bf16 v[42:45], v[158:161], v[228:231], v[42:45]
	v_mfma_f32_16x16x32_bf16 v[28:31], v[146:149], v[236:239], v[28:31]
	v_mfma_f32_16x16x32_bf16 v[24:27], v[158:161], v[236:239], v[24:27]
	v_mfma_f32_16x16x32_bf16 v[12:15], v[146:149], v[244:247], v[12:15]
	v_mfma_f32_16x16x32_bf16 v[8:11], v[158:161], v[244:247], v[8:11]
	s_setprio 0
	s_setprio 1
	v_mfma_f32_16x16x32_bf16 v[54:57], v[180:183], v[196:199], v[54:57]
	v_mfma_f32_16x16x32_bf16 v[50:53], v[188:191], v[196:199], v[50:53]
	v_mfma_f32_16x16x32_bf16 v[38:41], v[180:183], v[224:227], v[38:41]
	v_mfma_f32_16x16x32_bf16 v[34:37], v[188:191], v[224:227], v[34:37]
	v_mfma_f32_16x16x32_bf16 v[20:23], v[180:183], v[232:235], v[20:23]
	v_mfma_f32_16x16x32_bf16 v[16:19], v[188:191], v[232:235], v[16:19]
	v_mfma_f32_16x16x32_bf16 v[4:7], v[180:183], v[240:243], v[4:7]
	v_mfma_f32_16x16x32_bf16 v[0:3], v[188:191], v[240:243], v[0:3]
	v_mfma_f32_16x16x32_bf16 v[54:57], v[184:187], v[220:223], v[54:57]
	v_mfma_f32_16x16x32_bf16 v[50:53], v[192:195], v[220:223], v[50:53]
	v_mfma_f32_16x16x32_bf16 v[38:41], v[184:187], v[228:231], v[38:41]
	v_mfma_f32_16x16x32_bf16 v[34:37], v[192:195], v[228:231], v[34:37]
	v_mfma_f32_16x16x32_bf16 v[20:23], v[184:187], v[236:239], v[20:23]
	v_mfma_f32_16x16x32_bf16 v[16:19], v[192:195], v[236:239], v[16:19]
	v_mfma_f32_16x16x32_bf16 v[4:7], v[184:187], v[244:247], v[4:7]
	v_mfma_f32_16x16x32_bf16 v[0:3], v[192:195], v[244:247], v[0:3]
	s_setprio 0
	s_add_i32 s56, s56, 2
	s_add_u32 s30, s30, 0x100
	s_addc_u32 s31, s31, 0
	s_add_u32 s54, s54, 0x100
	s_addc_u32 s55, s55, 0
	s_add_u32 s34, s30, 0xfff80080
	s_addc_u32 s35, s31, -1
	s_add_i32 s57, 0, 0x10000
	s_cmp_eq_u32 s56, 28
	s_cselect_b32 s37, s25, s35
	s_cselect_b32 s36, s33, s34
	v_add_u32_e32 v153, s57, v150
	s_cselect_b32 s35, s17, s55
	s_cselect_b32 s34, s53, s54
	s_add_i32 s60, 0, 0x14000
	s_cmp_gt_u32 s56, 29
	s_barrier
	s_cbranch_scc0 .Lrot_735
	v_lshl_add_u32 v148, s22, 8, v33
	v_ashrrev_i32_e32 v149, 31, v148
	v_lshl_add_u64 v[144:145], v[148:149], 3, s[12:13]
	global_load_dwordx2 v[220:221], v[144:145], off
	global_load_dwordx2 v[222:223], v[144:145], off offset:128
	global_load_dwordx2 v[224:225], v[144:145], off offset:256
	global_load_dwordx2 v[226:227], v[144:145], off offset:384
	global_load_dwordx2 v[228:229], v[144:145], off offset:1024
	global_load_dwordx2 v[230:231], v[144:145], off offset:1152
	global_load_dwordx2 v[232:233], v[144:145], off offset:1280
	global_load_dwordx2 v[234:235], v[144:145], off offset:1408
	s_and_b64 vcc, exec, s[14:15]
	s_cbranch_vccz .LBB0_738
	s_barrier

; #define PG8_STAGE(bufoff, gbase, voff) do { _Pragma("unroll") for (int _i = 0; _i < 2; ++_i) \
;         __builtin_amdgcn_global_load_lds((const unsigned*)((const char*)(gbase) + (voff)[_i]), (PG8_LAS unsigned*)(lds + (bufoff) + ldsw + _i * 8192), 16, 0, 0); } while (0)
; #define PG8_WAIT_V(n) asm volatile("s_waitcnt vmcnt(" #n ")" ::: "memory")
; #define PG8_WAIT_L(n) asm volatile("s_waitcnt lgkmcnt(" #n ")" ::: "memory")
; #define PG8_BAR __builtin_amdgcn_s_barrier()
; #define PG8_SCHED __builtin_amdgcn_sched_barrier(0)
; template <class Epi, class Sched, bool ALIGN_EPI = false, bool SP2 = false, bool FP8 = false>
; __device__ __forceinline__ void gemm_phase(PG8_LAS unsigned char* lds, const Gemm g, const Sched& S, const Epi& E, const int tid) {
;     ...
;             PG8_LDB(B0, 0, 0); PG8_LDB(B1, 0, 1); PG8_SCHED; PG8_LDA(At, 0, 0); PG8_STAGE(PG8_SA(1, 1), a1 + hstepA, voffA);
;             PG8_WAIT_V(8); PG8_WAIT_L(0); PG8_BAR; PG8_MMA(0, 0, At, B0); PG8_MMA(0, 1, At, B1); PG8_BAR; PG8_SCHED;
.Lrot_801:
	ds_read_b128 v[130:133], v154
	ds_read_b128 v[134:137], v154 offset:1024
	ds_read_b128 v[138:141], v154 offset:2048
	ds_read_b128 v[154:157], v154 offset:3072
	ds_read_b128 v[158:161], v164
	ds_read_b128 v[180:183], v164 offset:1024
	ds_read_b128 v[184:187], v164 offset:2048
	ds_read_b128 v[190:193], v164 offset:3072
	v_lshl_add_u64 v[164:165], s[8:9], 0, v[150:151]
	s_add_i32 m0, s52, 0xc000
	ds_read_b128 v[194:197], v188
	ds_read_b128 v[198:201], v188 offset:1024
	ds_read_b128 v[220:223], v188 offset:2048
	ds_read_b128 v[224:227], v188 offset:3072
	ds_read_b128 v[228:231], v188 offset:4096
	ds_read_b128 v[232:235], v188 offset:5120
	ds_read_b128 v[236:239], v188 offset:6144
	ds_read_b128 v[240:243], v188 offset:7168
	global_load_lds_dwordx4 v[164:165], off
	v_lshl_add_u64 v[164:165], s[8:9], 0, v[152:153]
	s_add_i32 m0, s52, 0xe000
	s_nop 0
	global_load_lds_dwordx4 v[164:165], off
	s_cmp_eq_i32 s62, -2
	s_cbranch_scc1 .Lskw_5_0
	s_waitcnt vmcnt(8)

; #define PG8_STAGE(bufoff, gbase, voff) do { _Pragma("unroll") for (int _i = 0; _i < 2; ++_i) \
;         __builtin_amdgcn_global_load_lds((const unsigned*)((const char*)(gbase) + (voff)[_i]), (PG8_LAS unsigned*)(lds + (bufoff) + ldsw + _i * 8192), 16, 0, 0); } while (0)
; #define PG8_WAIT_V(n) asm volatile("s_waitcnt vmcnt(" #n ")" ::: "memory")
; #define PG8_WAIT_L(n) asm volatile("s_waitcnt lgkmcnt(" #n ")" ::: "memory")
; #define PG8_BAR __builtin_amdgcn_s_barrier()
; #define PG8_SCHED __builtin_amdgcn_sched_barrier(0)
; template <class Epi, class Sched, bool ALIGN_EPI = false, bool SP2 = false, bool FP8 = false>
; __device__ __forceinline__ void gemm_phase(PG8_LAS unsigned char* lds, const Gemm g, const Sched& S, const Epi& E, const int tid) {
;     ...
;             PG8_WAIT_V(8); PG8_WAIT_L(0); PG8_BAR; PG8_MMA(0, 0, At, B0); PG8_MMA(0, 1, At, B1); PG8_BAR; PG8_SCHED;
;             PG8_LDA(At, 0, 1); PG8_STAGE(PG8_SB(0, 0), b2, voffB); PG8_STAGE(PG8_SB(0, 1), b2 + hstepB, voffB); PG8_STAGE(PG8_SA(0, 0), a2, voffA);
;             PG8_WAIT_V(8); PG8_WAIT_L(0); PG8_BAR; PG8_MMA(1, 0, At, B0); PG8_MMA(1, 1, At, B1); PG8_BAR; PG8_SCHED;
;             PG8_LDB(B0, 1, 0); PG8_LDB(B1, 1, 1); PG8_SCHED; PG8_LDA(At, 1, 0); PG8_STAGE(PG8_SA(0, 1), a2 + hstepA, voffA);
;             PG8_WAIT_V(8); PG8_WAIT_L(0); PG8_BAR; PG8_MMA(0, 0, At, B0); PG8_MMA(0, 1, At, B1); PG8_BAR; PG8_SCHED;
.Lskw_5_1:
	s_waitcnt lgkmcnt(0)
	s_barrier
	s_setprio 1
	s_waitcnt lgkmcnt(0)
	v_mfma_f32_16x16x32_bf16 v[62:65], v[130:133], v[194:197], v[62:65]
	v_mfma_f32_16x16x32_bf16 v[58:61], v[138:141], v[194:197], v[58:61]
	v_mfma_f32_16x16x32_bf16 v[46:49], v[130:133], v[220:223], v[46:49]
	v_mfma_f32_16x16x32_bf16 v[42:45], v[138:141], v[220:223], v[42:45]
	v_mfma_f32_16x16x32_bf16 v[28:31], v[130:133], v[228:231], v[28:31]
	v_mfma_f32_16x16x32_bf16 v[24:27], v[138:141], v[228:231], v[24:27]
	v_mfma_f32_16x16x32_bf16 v[12:15], v[130:133], v[236:239], v[12:15]
	v_mfma_f32_16x16x32_bf16 v[8:11], v[138:141], v[236:239], v[8:11]
	v_mfma_f32_16x16x32_bf16 v[62:65], v[134:137], v[198:201], v[62:65]
	v_mfma_f32_16x16x32_bf16 v[58:61], v[154:157], v[198:201], v[58:61]
	v_mfma_f32_16x16x32_bf16 v[46:49], v[134:137], v[224:227], v[46:49]
	v_mfma_f32_16x16x32_bf16 v[42:45], v[154:157], v[224:227], v[42:45]
	v_mfma_f32_16x16x32_bf16 v[28:31], v[134:137], v[232:235], v[28:31]
	v_mfma_f32_16x16x32_bf16 v[24:27], v[154:157], v[232:235], v[24:27]
	v_mfma_f32_16x16x32_bf16 v[12:15], v[134:137], v[240:243], v[12:15]
	v_mfma_f32_16x16x32_bf16 v[8:11], v[154:157], v[240:243], v[8:11]
	s_setprio 0
	s_setprio 1
	v_mfma_f32_16x16x32_bf16 v[54:57], v[158:161], v[194:197], v[54:57]
	v_mfma_f32_16x16x32_bf16 v[50:53], v[184:187], v[194:197], v[50:53]
	v_mfma_f32_16x16x32_bf16 v[38:41], v[158:161], v[220:223], v[38:41]
	v_mfma_f32_16x16x32_bf16 v[34:37], v[184:187], v[220:223], v[34:37]
	v_mfma_f32_16x16x32_bf16 v[20:23], v[158:161], v[228:231], v[20:23]
	v_mfma_f32_16x16x32_bf16 v[16:19], v[184:187], v[228:231], v[16:19]
	v_mfma_f32_16x16x32_bf16 v[4:7], v[158:161], v[236:239], v[4:7]
	v_mfma_f32_16x16x32_bf16 v[0:3], v[184:187], v[236:239], v[0:3]
	v_mfma_f32_16x16x32_bf16 v[54:57], v[180:183], v[198:201], v[54:57]
	v_mfma_f32_16x16x32_bf16 v[50:53], v[190:193], v[198:201], v[50:53]
	v_mfma_f32_16x16x32_bf16 v[38:41], v[180:183], v[224:227], v[38:41]
	v_mfma_f32_16x16x32_bf16 v[34:37], v[190:193], v[224:227], v[34:37]
	v_mfma_f32_16x16x32_bf16 v[20:23], v[180:183], v[232:235], v[20:23]
	v_mfma_f32_16x16x32_bf16 v[16:19], v[190:193], v[232:235], v[16:19]
	v_mfma_f32_16x16x32_bf16 v[4:7], v[180:183], v[240:243], v[4:7]
	v_mfma_f32_16x16x32_bf16 v[0:3], v[190:193], v[240:243], v[0:3]
	s_setprio 0
	s_barrier
	s_add_i32 s63, 0, 0x18000
	s_add_i32 s64, 0, 0x1c000
	v_add_u32_e32 v154, s63, v163
	v_add_u32_e32 v189, s64, v163
	ds_read_b128 v[130:133], v154
	ds_read_b128 v[134:137], v154 offset:1024
	ds_read_b128 v[138:141], v154 offset:2048
	ds_read_b128 v[154:157], v154 offset:3072
	ds_read_b128 v[158:161], v189
	ds_read_b128 v[180:183], v189 offset:1024
	ds_read_b128 v[184:187], v189 offset:2048
	ds_read_b128 v[190:193], v189 offset:3072
	s_add_u32 s46, s46, 0x200000
	s_addc_u32 s47, s47, 0
	s_mov_b32 m0, s54
	v_lshl_add_u64 v[248:249], s[46:47], 0, v[148:149]
	ds_read_b128 v[194:197], v188 offset:32768
	ds_read_b128 v[198:201], v188 offset:33792
	ds_read_b128 v[220:223], v188 offset:34816
	ds_read_b128 v[224:227], v188 offset:35840
	ds_read_b128 v[228:231], v188 offset:36864
	ds_read_b128 v[232:235], v188 offset:37888
	ds_read_b128 v[236:239], v188 offset:38912
	ds_read_b128 v[240:243], v188 offset:39936
	global_load_lds_dwordx4 v[248:249], off
	v_lshl_add_u64 v[248:249], s[46:47], 0, v[144:145]
	s_mov_b32 m0, s55
	s_nop 0
	global_load_lds_dwordx4 v[248:249], off
	s_waitcnt vmcnt(8)
	s_waitcnt lgkmcnt(0)
	s_barrier
	s_setprio 1
	s_waitcnt lgkmcnt(0)
	v_mfma_f32_16x16x32_bf16 v[126:129], v[130:133], v[194:197], v[126:129]
	v_mfma_f32_16x16x32_bf16 v[122:125], v[138:141], v[194:197], v[122:125]
	v_mfma_f32_16x16x32_bf16 v[110:113], v[130:133], v[220:223], v[110:113]
	v_mfma_f32_16x16x32_bf16 v[106:109], v[138:141], v[220:223], v[106:109]
	v_mfma_f32_16x16x32_bf16 v[94:97], v[130:133], v[228:231], v[94:97]
	v_mfma_f32_16x16x32_bf16 v[90:93], v[138:141], v[228:231], v[90:93]
	v_mfma_f32_16x16x32_bf16 v[78:81], v[130:133], v[236:239], v[78:81]
	v_mfma_f32_16x16x32_bf16 v[74:77], v[138:141], v[236:239], v[74:77]
	v_mfma_f32_16x16x32_bf16 v[126:129], v[134:137], v[198:201], v[126:129]
	v_mfma_f32_16x16x32_bf16 v[122:125], v[154:157], v[198:201], v[122:125]
	v_mfma_f32_16x16x32_bf16 v[110:113], v[134:137], v[224:227], v[110:113]
	v_mfma_f32_16x16x32_bf16 v[106:109], v[154:157], v[224:227], v[106:109]
	v_mfma_f32_16x16x32_bf16 v[94:97], v[134:137], v[232:235], v[94:97]
	v_mfma_f32_16x16x32_bf16 v[90:93], v[154:157], v[232:235], v[90:93]
	v_mfma_f32_16x16x32_bf16 v[78:81], v[134:137], v[240:243], v[78:81]
	v_mfma_f32_16x16x32_bf16 v[74:77], v[154:157], v[240:243], v[74:77]
	s_setprio 0
	s_setprio 1
	v_mfma_f32_16x16x32_bf16 v[118:121], v[158:161], v[194:197], v[118:121]
	v_mfma_f32_16x16x32_bf16 v[114:117], v[184:187], v[194:197], v[114:117]
	v_mfma_f32_16x16x32_bf16 v[102:105], v[158:161], v[220:223], v[102:105]
	v_mfma_f32_16x16x32_bf16 v[98:101], v[184:187], v[220:223], v[98:101]
	v_mfma_f32_16x16x32_bf16 v[86:89], v[158:161], v[228:231], v[86:89]
	v_mfma_f32_16x16x32_bf16 v[82:85], v[184:187], v[228:231], v[82:85]
	v_mfma_f32_16x16x32_bf16 v[70:73], v[158:161], v[236:239], v[70:73]
	v_mfma_f32_16x16x32_bf16 v[66:69], v[184:187], v[236:239], v[66:69]
	v_mfma_f32_16x16x32_bf16 v[118:121], v[180:183], v[198:201], v[118:121]
	v_mfma_f32_16x16x32_bf16 v[114:117], v[190:193], v[198:201], v[114:117]
	v_mfma_f32_16x16x32_bf16 v[102:105], v[180:183], v[224:227], v[102:105]
	v_mfma_f32_16x16x32_bf16 v[98:101], v[190:193], v[224:227], v[98:101]
	v_mfma_f32_16x16x32_bf16 v[86:89], v[180:183], v[232:235], v[86:89]
	v_mfma_f32_16x16x32_bf16 v[82:85], v[190:193], v[232:235], v[82:85]
	v_mfma_f32_16x16x32_bf16 v[70:73], v[180:183], v[240:243], v[70:73]
	v_mfma_f32_16x16x32_bf16 v[66:69], v[190:193], v[240:243], v[66:69]
	s_setprio 0
	s_barrier
; #define PG8_STAGE(bufoff, gbase, voff) do { _Pragma("unroll") for (int _i = 0; _i < 2; ++_i) \
;         __builtin_amdgcn_global_load_lds((const unsigned*)((const char*)(gbase) + (voff)[_i]), (PG8_LAS unsigned*)(lds + (bufoff) + ldsw + _i * 8192), 16, 0, 0); } while (0)
; #define PG8_WAIT_V(n) asm volatile("s_waitcnt vmcnt(" #n ")" ::: "memory")
; #define PG8_WAIT_L(n) asm volatile("s_waitcnt lgkmcnt(" #n ")" ::: "memory")
; #define PG8_BAR __builtin_amdgcn_s_barrier()
; #define PG8_SCHED __builtin_amdgcn_sched_barrier(0)
; template <class Epi, class Sched, bool ALIGN_EPI = false, bool SP2 = false, bool FP8 = false>
; __device__ __forceinline__ void gemm_phase(PG8_LAS unsigned char* lds, const Gemm g, const Sched& S, const Epi& E, const int tid) {
;     ...
;         for (int t = 0; t < nt; t += 2) {
;             const bool last = (t == nt - 2);
;             const char* a1 = cA + (size_t)(t + 1) * kstep;
;             const char* a2 = last ? nA : cA + (size_t)(t + 2) * kstep; const char* b2 = last ? nB : cB + (size_t)(t + 2) * kstep;
;             const char* a3 = a2 + kstep; const char* b3 = b2 + kstep;
;             if (last && has_next) S.a_ready(nxt);
;     ...
;             PG8_WAIT_V(8); PG8_WAIT_L(0); PG8_BAR; PG8_MMA(0, 0, At, B0); PG8_MMA(0, 1, At, B1); PG8_BAR; PG8_SCHED;
;             PG8_LDA(At, 1, 1); PG8_STAGE(PG8_SB(1, 0), b3, voffB); PG8_STAGE(PG8_SB(1, 1), b3 + hstepB, voffB); PG8_STAGE(PG8_SA(1, 0), a3, voffA);
;             PG8_WAIT_V(8); PG8_WAIT_L(0); PG8_BAR; PG8_MMA(1, 0, At, B0); PG8_MMA(1, 1, At, B1); PG8_BAR; PG8_SCHED;
	s_add_i32 s46, s63, s51
	v_lshl_add_u64 v[164:165], v[164:165], 0, s[38:39]
	s_mov_b32 m0, s46
	ds_read_b128 v[194:197], v188 offset:49152
	ds_read_b128 v[198:201], v188 offset:50176
	ds_read_b128 v[220:223], v188 offset:51200
	ds_read_b128 v[224:227], v188 offset:52224
	ds_read_b128 v[228:231], v188 offset:53248
	ds_read_b128 v[232:235], v188 offset:54272
	ds_read_b128 v[236:239], v188 offset:55296
	ds_read_b128 v[240:243], v188 offset:56320
	global_load_lds_dwordx4 v[164:165], off
	s_add_i32 m0, s46, 0x2000
	s_add_u32 s10, s10, 0x200080
	v_lshl_add_u64 v[164:165], v[166:167], 0, s[38:39]
	s_addc_u32 s11, s11, 0
	s_add_i32 s46, s64, s51
	global_load_lds_dwordx4 v[164:165], off
	v_lshl_add_u64 v[164:165], s[10:11], 0, v[146:147]
	s_mov_b32 m0, s46
	s_nop 0
	global_load_lds_dwordx4 v[164:165], off
	v_lshl_add_u64 v[164:165], s[10:11], 0, v[142:143]
	s_add_i32 m0, s46, 0x2000
	s_nop 0
	global_load_lds_dwordx4 v[164:165], off
	v_lshl_add_u64 v[164:165], v[244:245], 0, s[38:39]
	s_mov_b32 m0, s56
	s_nop 0
	global_load_lds_dwordx4 v[164:165], off
	v_lshl_add_u64 v[164:165], v[246:247], 0, s[38:39]
	s_mov_b32 m0, s57
	s_nop 0
	global_load_lds_dwordx4 v[164:165], off
	s_waitcnt vmcnt(8)
	s_waitcnt lgkmcnt(0)
	s_barrier
	s_setprio 1
	s_waitcnt lgkmcnt(0)
	v_mfma_f32_16x16x32_bf16 v[62:65], v[130:133], v[194:197], v[62:65]
	v_mfma_f32_16x16x32_bf16 v[58:61], v[138:141], v[194:197], v[58:61]
	v_mfma_f32_16x16x32_bf16 v[46:49], v[130:133], v[220:223], v[46:49]
	v_mfma_f32_16x16x32_bf16 v[42:45], v[138:141], v[220:223], v[42:45]
	v_mfma_f32_16x16x32_bf16 v[28:31], v[130:133], v[228:231], v[28:31]
	v_mfma_f32_16x16x32_bf16 v[24:27], v[138:141], v[228:231], v[24:27]
	v_mfma_f32_16x16x32_bf16 v[12:15], v[130:133], v[236:239], v[12:15]
	v_mfma_f32_16x16x32_bf16 v[8:11], v[138:141], v[236:239], v[8:11]
	v_mfma_f32_16x16x32_bf16 v[62:65], v[134:137], v[198:201], v[62:65]
	v_mfma_f32_16x16x32_bf16 v[58:61], v[154:157], v[198:201], v[58:61]
	v_mfma_f32_16x16x32_bf16 v[46:49], v[134:137], v[224:227], v[46:49]
	v_mfma_f32_16x16x32_bf16 v[42:45], v[154:157], v[224:227], v[42:45]
	v_mfma_f32_16x16x32_bf16 v[28:31], v[134:137], v[232:235], v[28:31]
	v_mfma_f32_16x16x32_bf16 v[24:27], v[154:157], v[232:235], v[24:27]
	v_mfma_f32_16x16x32_bf16 v[12:15], v[134:137], v[240:243], v[12:15]
	v_mfma_f32_16x16x32_bf16 v[8:11], v[154:157], v[240:243], v[8:11]
	s_setprio 0
	s_setprio 1
	v_mfma_f32_16x16x32_bf16 v[54:57], v[158:161], v[194:197], v[54:57]
	v_mfma_f32_16x16x32_bf16 v[50:53], v[184:187], v[194:197], v[50:53]
	v_mfma_f32_16x16x32_bf16 v[38:41], v[158:161], v[220:223], v[38:41]
	v_mfma_f32_16x16x32_bf16 v[34:37], v[184:187], v[220:223], v[34:37]
	v_mfma_f32_16x16x32_bf16 v[20:23], v[158:161], v[228:231], v[20:23]
	v_mfma_f32_16x16x32_bf16 v[16:19], v[184:187], v[228:231], v[16:19]
	v_mfma_f32_16x16x32_bf16 v[4:7], v[158:161], v[236:239], v[4:7]
	v_mfma_f32_16x16x32_bf16 v[0:3], v[184:187], v[236:239], v[0:3]
	v_mfma_f32_16x16x32_bf16 v[54:57], v[180:183], v[198:201], v[54:57]
	v_mfma_f32_16x16x32_bf16 v[50:53], v[190:193], v[198:201], v[50:53]
	v_mfma_f32_16x16x32_bf16 v[38:41], v[180:183], v[224:227], v[38:41]
	v_mfma_f32_16x16x32_bf16 v[34:37], v[190:193], v[224:227], v[34:37]
	v_mfma_f32_16x16x32_bf16 v[20:23], v[180:183], v[232:235], v[20:23]
	v_mfma_f32_16x16x32_bf16 v[16:19], v[190:193], v[232:235], v[16:19]
	v_mfma_f32_16x16x32_bf16 v[4:7], v[180:183], v[240:243], v[4:7]
	v_mfma_f32_16x16x32_bf16 v[0:3], v[190:193], v[240:243], v[0:3]
	s_setprio 0
	s_add_i32 s62, s62, 2
	s_add_u32 s8, s8, 0x100
	s_addc_u32 s9, s9, 0
	s_add_u32 s60, s60, 0x100
	s_addc_u32 s61, s61, 0
	s_add_u32 s10, s8, 0xffe00080
	s_addc_u32 s11, s9, -1
	s_add_i32 s63, 0, 0x10000
	s_cmpk_eq_i32 s62, 0x7c
	s_cselect_b32 s47, s33, s11
	s_cselect_b32 s46, s41, s10
	s_cselect_b32 s11, s37, s61
	s_cselect_b32 s10, s59, s60
	s_add_i32 s66, 0, 0x14000
	v_add_u32_e32 v154, s63, v163
	v_add_u32_e32 v164, s66, v163
	s_cmpk_gt_u32 s62, 0x7d
	s_barrier
	s_cbranch_scc0 .Lrot_801
	s_and_b64 vcc, exec, s[30:31]
	s_cbranch_vccz .LBB0_804
	s_barrier
